# write-through (sc1) on all 16-byte global stores so the grid-barrier L2 writeback has less to flush
# baseline (speedup 1.0000x reference)
; __device__ __forceinline__ unsigned pk2(float lo, float hi) { const f32x2_ v = {lo, hi}; return __builtin_bit_cast(unsigned, __builtin_convertvector(v, bf16x2_)); }
; __device__ __forceinline__ void ln_phase(const PP P, const float* g, const float* bta) {
;     ...
;     for (int row = P.bid * 8 + wave; row < MT; row += G * 8) {
;         float* p = X + (size_t)row * 1024; f32x4 v[4]; float s = 0.f;
; #pragma unroll
;         for (int i = 0; i < 4; ++i) { v[i] = *(const f32x4*)(p + 256 * i + lane * 4); s += (v[i][0] + v[i][1]) + (v[i][2] + v[i][3]); }
;         const float mu = wave_sum(s) * (1.0f / 1024.0f); float q = 0.f;
; #pragma unroll
;         for (int i = 0; i < 4; ++i) { const f32x4 d = v[i] - mu; q += (d[0] * d[0] + d[1] * d[1]) + (d[2] * d[2] + d[3] * d[3]); }
;         const float rstd = __builtin_amdgcn_rsqf(wave_sum(q) * (1.0f / 1024.0f) + 1e-5f);
; #pragma unroll
;         for (int i = 0; i < 4; ++i) { const int col = 256 * i + lane * 4; const f32x4 gg = *(const f32x4*)(g + col), bb = *(const f32x4*)(bta + col);
;             const f32x4 y = (v[i] - mu) * rstd * gg + bb; *(f32x4*)(p + col) = y;
;             u32x2 w; w.x = pk2(y[0], y[1]); w.y = pk2(y[2], y[3]); *(u32x2*)(XB + (size_t)row * 1024 + col) = w; }
;     }
.Lln10_h0:
	s_cmp_ge_u32 s13, 0x8200
	s_cbranch_scc1 .Lln10_done
	s_waitcnt vmcnt(4)
	v_pk_add_f32 v[70:71], v[4:5], v[6:7]
	v_pk_add_f32 v[72:73], v[8:9], v[10:11]
	v_pk_add_f32 v[74:75], v[12:13], v[14:15]
	v_pk_add_f32 v[76:77], v[16:17], v[18:19]
	v_pk_add_f32 v[70:71], v[70:71], v[72:73]
	v_pk_add_f32 v[74:75], v[74:75], v[76:77]
	v_pk_add_f32 v[70:71], v[70:71], v[74:75]
	s_nop 0
	v_add_f32_e32 v70, v70, v71
	s_nop 1
	v_add_f32_dpp v70, v70, v70 quad_perm:[1,0,3,2] row_mask:0xf bank_mask:0xf bound_ctrl:1
	s_nop 1
	v_add_f32_dpp v70, v70, v70 quad_perm:[2,3,0,1] row_mask:0xf bank_mask:0xf bound_ctrl:1
	s_nop 1
	v_add_f32_dpp v70, v70, v70 row_half_mirror row_mask:0xf bank_mask:0xf bound_ctrl:1
	s_nop 1
	v_add_f32_dpp v70, v70, v70 row_mirror row_mask:0xf bank_mask:0xf bound_ctrl:1
	s_nop 1
	v_readlane_b32 s3, v70, 16
	v_readlane_b32 s9, v70, 48
	v_readlane_b32 s2, v70, 0
	v_readlane_b32 s8, v70, 32
	s_nop 1
	v_mov_b32_e32 v76, s3
	v_mov_b32_e32 v77, s9
	v_add_f32_e32 v76, s2, v76
	v_add_f32_e32 v77, s8, v77
	v_add_f32_e32 v70, v76, v77
	v_fmac_f32_e32 v4, 0xba800000, v70
	v_fmac_f32_e32 v5, 0xba800000, v70
	v_fmac_f32_e32 v6, 0xba800000, v70
	v_fmac_f32_e32 v7, 0xba800000, v70
	v_fmac_f32_e32 v8, 0xba800000, v70
	v_fmac_f32_e32 v9, 0xba800000, v70
	v_fmac_f32_e32 v10, 0xba800000, v70
	v_fmac_f32_e32 v11, 0xba800000, v70
	v_fmac_f32_e32 v12, 0xba800000, v70
	v_fmac_f32_e32 v13, 0xba800000, v70
	v_fmac_f32_e32 v14, 0xba800000, v70
	v_fmac_f32_e32 v15, 0xba800000, v70
	v_fmac_f32_e32 v16, 0xba800000, v70
	v_fmac_f32_e32 v17, 0xba800000, v70
	v_fmac_f32_e32 v18, 0xba800000, v70
	v_fmac_f32_e32 v19, 0xba800000, v70
	v_pk_mul_f32 v[72:73], v[4:5], v[4:5]
	v_pk_mul_f32 v[74:75], v[6:7], v[6:7]
	v_pk_fma_f32 v[72:73], v[8:9], v[8:9], v[72:73]
	v_pk_fma_f32 v[74:75], v[10:11], v[10:11], v[74:75]
	v_pk_fma_f32 v[72:73], v[12:13], v[12:13], v[72:73]
	v_pk_fma_f32 v[74:75], v[14:15], v[14:15], v[74:75]
	v_pk_fma_f32 v[72:73], v[16:17], v[16:17], v[72:73]
	v_pk_fma_f32 v[74:75], v[18:19], v[18:19], v[74:75]
	v_pk_add_f32 v[72:73], v[72:73], v[74:75]
	s_nop 0
	v_add_f32_e32 v71, v72, v73
	s_nop 1
	v_add_f32_dpp v71, v71, v71 quad_perm:[1,0,3,2] row_mask:0xf bank_mask:0xf bound_ctrl:1
	s_nop 1
	v_add_f32_dpp v71, v71, v71 quad_perm:[2,3,0,1] row_mask:0xf bank_mask:0xf bound_ctrl:1
	s_nop 1
	v_add_f32_dpp v71, v71, v71 row_half_mirror row_mask:0xf bank_mask:0xf bound_ctrl:1
	s_nop 1
	v_add_f32_dpp v71, v71, v71 row_mirror row_mask:0xf bank_mask:0xf bound_ctrl:1
	s_nop 1
	v_readlane_b32 s3, v71, 16
	v_readlane_b32 s9, v71, 48
	v_readlane_b32 s2, v71, 0
	v_readlane_b32 s8, v71, 32
	s_nop 1
	v_mov_b32_e32 v76, s3
	v_mov_b32_e32 v77, s9
	v_add_f32_e32 v76, s2, v76
	v_add_f32_e32 v77, s8, v77
	v_add_f32_e32 v71, v76, v77
	v_fmamk_f32 v71, v71, 0x3a800000, v164
	v_rsq_f32_e32 v72, v71
	s_nop 1
	v_pk_mul_f32 v[4:5], v[4:5], v[72:73] op_sel_hi:[1,0]
	v_pk_mul_f32 v[6:7], v[6:7], v[72:73] op_sel_hi:[1,0]
	v_pk_mul_f32 v[8:9], v[8:9], v[72:73] op_sel_hi:[1,0]
	v_pk_mul_f32 v[10:11], v[10:11], v[72:73] op_sel_hi:[1,0]
	v_pk_mul_f32 v[12:13], v[12:13], v[72:73] op_sel_hi:[1,0]
	v_pk_mul_f32 v[14:15], v[14:15], v[72:73] op_sel_hi:[1,0]
	v_pk_mul_f32 v[16:17], v[16:17], v[72:73] op_sel_hi:[1,0]
	v_pk_mul_f32 v[18:19], v[18:19], v[72:73] op_sel_hi:[1,0]
	v_pk_fma_f32 v[42:43], v[4:5], v[100:101], v[116:117]
	v_pk_fma_f32 v[44:45], v[6:7], v[102:103], v[118:119]
	v_pk_fma_f32 v[46:47], v[8:9], v[104:105], v[120:121]
	v_pk_fma_f32 v[48:49], v[10:11], v[106:107], v[122:123]
	v_pk_fma_f32 v[50:51], v[12:13], v[108:109], v[124:125]
	v_pk_fma_f32 v[52:53], v[14:15], v[110:111], v[126:127]
	v_pk_fma_f32 v[54:55], v[16:17], v[112:113], v[128:129]
	v_pk_fma_f32 v[56:57], v[18:19], v[114:115], v[130:131]
	s_lshl_b32 s12, s20, 1
	s_add_u32 s12, s13, s12
	s_lshl_b32 s90, s20, 13
	s_add_u32 s18, s10, s90
	s_addc_u32 s19, s11, 0
	s_cmp_lt_u32 s12, 0x8200
	s_cselect_b32 s18, s18, s10
	s_cselect_b32 s19, s19, s11
	global_load_dwordx4 v[4:7], v1, s[18:19]
	global_load_dwordx4 v[8:11], v1, s[18:19] offset:1024
	global_load_dwordx4 v[12:15], v1, s[18:19] offset:2048
	global_load_dwordx4 v[16:19], v1, s[18:19] offset:3072
	v_cvt_pk_bf16_f32 v58, v42, v43
	v_cvt_pk_bf16_f32 v59, v44, v45
	v_cvt_pk_bf16_f32 v60, v46, v47
	v_cvt_pk_bf16_f32 v61, v48, v49
	v_cvt_pk_bf16_f32 v62, v50, v51
	v_cvt_pk_bf16_f32 v63, v52, v53
	v_cvt_pk_bf16_f32 v64, v54, v55
	v_cvt_pk_bf16_f32 v65, v56, v57
	global_store_dwordx4 v1, v[42:45], s[10:11] sc1
	global_store_dwordx4 v1, v[46:49], s[10:11] offset:1024 sc1
	global_store_dwordx4 v1, v[50:53], s[10:11] offset:2048 sc1
	global_store_dwordx4 v1, v[54:57], s[10:11] offset:3072 sc1
	global_store_dwordx2 v2, v[58:59], s[14:15]
	global_store_dwordx2 v2, v[60:61], s[14:15] offset:512
	global_store_dwordx2 v2, v[62:63], s[14:15] offset:1024
	global_store_dwordx2 v2, v[64:65], s[14:15] offset:1536
	s_add_u32 s13, s13, s20
	s_lshl_b32 s90, s20, 12
	s_add_u32 s10, s10, s90
	s_addc_u32 s11, s11, 0
	s_lshl_b32 s90, s20, 11
	s_add_u32 s14, s14, s90
	s_addc_u32 s15, s15, 0
; __device__ __forceinline__ unsigned pk2(float lo, float hi) { const f32x2_ v = {lo, hi}; return __builtin_bit_cast(unsigned, __builtin_convertvector(v, bf16x2_)); }
; __device__ __forceinline__ void ln_phase(const PP P, const float* g, const float* bta) {
;     ...
;     for (int row = P.bid * 8 + wave; row < MT; row += G * 8) {
;         float* p = X + (size_t)row * 1024; f32x4 v[4]; float s = 0.f;
; #pragma unroll
;         for (int i = 0; i < 4; ++i) { v[i] = *(const f32x4*)(p + 256 * i + lane * 4); s += (v[i][0] + v[i][1]) + (v[i][2] + v[i][3]); }
;         const float mu = wave_sum(s) * (1.0f / 1024.0f); float q = 0.f;
; #pragma unroll
;         for (int i = 0; i < 4; ++i) { const f32x4 d = v[i] - mu; q += (d[0] * d[0] + d[1] * d[1]) + (d[2] * d[2] + d[3] * d[3]); }
;         const float rstd = __builtin_amdgcn_rsqf(wave_sum(q) * (1.0f / 1024.0f) + 1e-5f);
; #pragma unroll
;         for (int i = 0; i < 4; ++i) { const int col = 256 * i + lane * 4; const f32x4 gg = *(const f32x4*)(g + col), bb = *(const f32x4*)(bta + col);
;             const f32x4 y = (v[i] - mu) * rstd * gg + bb; *(f32x4*)(p + col) = y;
;             u32x2 w; w.x = pk2(y[0], y[1]); w.y = pk2(y[2], y[3]); *(u32x2*)(XB + (size_t)row * 1024 + col) = w; }
;     }
.Lln10_loopB:
	s_cmp_ge_u32 s13, 0x8200
	s_cbranch_scc1 .Lln10_done
	s_waitcnt vmcnt(12)
	v_pk_add_f32 v[70:71], v[26:27], v[28:29]
	v_pk_add_f32 v[72:73], v[30:31], v[32:33]
	v_pk_add_f32 v[74:75], v[34:35], v[36:37]
	v_pk_add_f32 v[76:77], v[38:39], v[40:41]
	v_pk_add_f32 v[70:71], v[70:71], v[72:73]
	v_pk_add_f32 v[74:75], v[74:75], v[76:77]
	v_pk_add_f32 v[70:71], v[70:71], v[74:75]
	s_nop 0
	v_add_f32_e32 v70, v70, v71
	s_nop 1
	v_add_f32_dpp v70, v70, v70 quad_perm:[1,0,3,2] row_mask:0xf bank_mask:0xf bound_ctrl:1
	s_nop 1
	v_add_f32_dpp v70, v70, v70 quad_perm:[2,3,0,1] row_mask:0xf bank_mask:0xf bound_ctrl:1
	s_nop 1
	v_add_f32_dpp v70, v70, v70 row_half_mirror row_mask:0xf bank_mask:0xf bound_ctrl:1
	s_nop 1
	v_add_f32_dpp v70, v70, v70 row_mirror row_mask:0xf bank_mask:0xf bound_ctrl:1
	s_nop 1
	v_readlane_b32 s3, v70, 16
	v_readlane_b32 s9, v70, 48
	v_readlane_b32 s2, v70, 0
	v_readlane_b32 s8, v70, 32
	s_nop 1
	v_mov_b32_e32 v76, s3
	v_mov_b32_e32 v77, s9
	v_add_f32_e32 v76, s2, v76
	v_add_f32_e32 v77, s8, v77
	v_add_f32_e32 v70, v76, v77
	v_fmac_f32_e32 v26, 0xba800000, v70
	v_fmac_f32_e32 v27, 0xba800000, v70
	v_fmac_f32_e32 v28, 0xba800000, v70
	v_fmac_f32_e32 v29, 0xba800000, v70
	v_fmac_f32_e32 v30, 0xba800000, v70
	v_fmac_f32_e32 v31, 0xba800000, v70
	v_fmac_f32_e32 v32, 0xba800000, v70
	v_fmac_f32_e32 v33, 0xba800000, v70
	v_fmac_f32_e32 v34, 0xba800000, v70
	v_fmac_f32_e32 v35, 0xba800000, v70
	v_fmac_f32_e32 v36, 0xba800000, v70
	v_fmac_f32_e32 v37, 0xba800000, v70
	v_fmac_f32_e32 v38, 0xba800000, v70
	v_fmac_f32_e32 v39, 0xba800000, v70
	v_fmac_f32_e32 v40, 0xba800000, v70
	v_fmac_f32_e32 v41, 0xba800000, v70
	v_pk_mul_f32 v[72:73], v[26:27], v[26:27]
	v_pk_mul_f32 v[74:75], v[28:29], v[28:29]
	v_pk_fma_f32 v[72:73], v[30:31], v[30:31], v[72:73]
	v_pk_fma_f32 v[74:75], v[32:33], v[32:33], v[74:75]
	v_pk_fma_f32 v[72:73], v[34:35], v[34:35], v[72:73]
	v_pk_fma_f32 v[74:75], v[36:37], v[36:37], v[74:75]
	v_pk_fma_f32 v[72:73], v[38:39], v[38:39], v[72:73]
	v_pk_fma_f32 v[74:75], v[40:41], v[40:41], v[74:75]
	v_pk_add_f32 v[72:73], v[72:73], v[74:75]
	s_nop 0
	v_add_f32_e32 v71, v72, v73
	s_nop 1
	v_add_f32_dpp v71, v71, v71 quad_perm:[1,0,3,2] row_mask:0xf bank_mask:0xf bound_ctrl:1
	s_nop 1
	v_add_f32_dpp v71, v71, v71 quad_perm:[2,3,0,1] row_mask:0xf bank_mask:0xf bound_ctrl:1
	s_nop 1
	v_add_f32_dpp v71, v71, v71 row_half_mirror row_mask:0xf bank_mask:0xf bound_ctrl:1
	s_nop 1
	v_add_f32_dpp v71, v71, v71 row_mirror row_mask:0xf bank_mask:0xf bound_ctrl:1
	s_nop 1
	v_readlane_b32 s3, v71, 16
	v_readlane_b32 s9, v71, 48
	v_readlane_b32 s2, v71, 0
	v_readlane_b32 s8, v71, 32
	s_nop 1
	v_mov_b32_e32 v76, s3
	v_mov_b32_e32 v77, s9
	v_add_f32_e32 v76, s2, v76
	v_add_f32_e32 v77, s8, v77
	v_add_f32_e32 v71, v76, v77
	v_fmamk_f32 v71, v71, 0x3a800000, v164
	v_rsq_f32_e32 v72, v71
	s_nop 1
	v_pk_mul_f32 v[26:27], v[26:27], v[72:73] op_sel_hi:[1,0]
	v_pk_mul_f32 v[28:29], v[28:29], v[72:73] op_sel_hi:[1,0]
	v_pk_mul_f32 v[30:31], v[30:31], v[72:73] op_sel_hi:[1,0]
	v_pk_mul_f32 v[32:33], v[32:33], v[72:73] op_sel_hi:[1,0]
	v_pk_mul_f32 v[34:35], v[34:35], v[72:73] op_sel_hi:[1,0]
	v_pk_mul_f32 v[36:37], v[36:37], v[72:73] op_sel_hi:[1,0]
	v_pk_mul_f32 v[38:39], v[38:39], v[72:73] op_sel_hi:[1,0]
	v_pk_mul_f32 v[40:41], v[40:41], v[72:73] op_sel_hi:[1,0]
	v_pk_fma_f32 v[42:43], v[26:27], v[100:101], v[116:117]
	v_pk_fma_f32 v[44:45], v[28:29], v[102:103], v[118:119]
	v_pk_fma_f32 v[46:47], v[30:31], v[104:105], v[120:121]
	v_pk_fma_f32 v[48:49], v[32:33], v[106:107], v[122:123]
	v_pk_fma_f32 v[50:51], v[34:35], v[108:109], v[124:125]
	v_pk_fma_f32 v[52:53], v[36:37], v[110:111], v[126:127]
	v_pk_fma_f32 v[54:55], v[38:39], v[112:113], v[128:129]
	v_pk_fma_f32 v[56:57], v[40:41], v[114:115], v[130:131]
	s_lshl_b32 s12, s20, 1
	s_add_u32 s12, s13, s12
	s_lshl_b32 s90, s20, 13
	s_add_u32 s18, s10, s90
	s_addc_u32 s19, s11, 0
	s_cmp_lt_u32 s12, 0x8200
	s_cselect_b32 s18, s18, s10
	s_cselect_b32 s19, s19, s11
	global_load_dwordx4 v[26:29], v1, s[18:19]
	global_load_dwordx4 v[30:33], v1, s[18:19] offset:1024
	global_load_dwordx4 v[34:37], v1, s[18:19] offset:2048
	global_load_dwordx4 v[38:41], v1, s[18:19] offset:3072
	v_cvt_pk_bf16_f32 v58, v42, v43
	v_cvt_pk_bf16_f32 v59, v44, v45
	v_cvt_pk_bf16_f32 v60, v46, v47
	v_cvt_pk_bf16_f32 v61, v48, v49
	v_cvt_pk_bf16_f32 v62, v50, v51
	v_cvt_pk_bf16_f32 v63, v52, v53
	v_cvt_pk_bf16_f32 v64, v54, v55
	v_cvt_pk_bf16_f32 v65, v56, v57
	global_store_dwordx4 v1, v[42:45], s[10:11] sc1
	global_store_dwordx4 v1, v[46:49], s[10:11] offset:1024 sc1
	global_store_dwordx4 v1, v[50:53], s[10:11] offset:2048 sc1
	global_store_dwordx4 v1, v[54:57], s[10:11] offset:3072 sc1
	global_store_dwordx2 v2, v[58:59], s[14:15]
	global_store_dwordx2 v2, v[60:61], s[14:15] offset:512
	global_store_dwordx2 v2, v[62:63], s[14:15] offset:1024
	global_store_dwordx2 v2, v[64:65], s[14:15] offset:1536
	s_add_u32 s13, s13, s20
	s_lshl_b32 s90, s20, 12
	s_add_u32 s10, s10, s90
	s_addc_u32 s11, s11, 0
	s_lshl_b32 s90, s20, 11
	s_add_u32 s14, s14, s90
	s_addc_u32 s15, s15, 0
; __device__ __forceinline__ unsigned pk2(float lo, float hi) { const f32x2_ v = {lo, hi}; return __builtin_bit_cast(unsigned, __builtin_convertvector(v, bf16x2_)); }
; __device__ __forceinline__ void ln_phase(const PP P, const float* g, const float* bta) {
;     ...
;     for (int row = P.bid * 8 + wave; row < MT; row += G * 8) {
;         float* p = X + (size_t)row * 1024; f32x4 v[4]; float s = 0.f;
; #pragma unroll
;         for (int i = 0; i < 4; ++i) { v[i] = *(const f32x4*)(p + 256 * i + lane * 4); s += (v[i][0] + v[i][1]) + (v[i][2] + v[i][3]); }
;         const float mu = wave_sum(s) * (1.0f / 1024.0f); float q = 0.f;
; #pragma unroll
;         for (int i = 0; i < 4; ++i) { const f32x4 d = v[i] - mu; q += (d[0] * d[0] + d[1] * d[1]) + (d[2] * d[2] + d[3] * d[3]); }
;         const float rstd = __builtin_amdgcn_rsqf(wave_sum(q) * (1.0f / 1024.0f) + 1e-5f);
; #pragma unroll
;         for (int i = 0; i < 4; ++i) { const int col = 256 * i + lane * 4; const f32x4 gg = *(const f32x4*)(g + col), bb = *(const f32x4*)(bta + col);
;             const f32x4 y = (v[i] - mu) * rstd * gg + bb; *(f32x4*)(p + col) = y;
;             u32x2 w; w.x = pk2(y[0], y[1]); w.y = pk2(y[2], y[3]); *(u32x2*)(XB + (size_t)row * 1024 + col) = w; }
;     }
.Lln10_loopA:
	s_cmp_ge_u32 s13, 0x8200
	s_cbranch_scc1 .Lln10_done
	s_waitcnt vmcnt(12)
	v_pk_add_f32 v[70:71], v[4:5], v[6:7]
	v_pk_add_f32 v[72:73], v[8:9], v[10:11]
	v_pk_add_f32 v[74:75], v[12:13], v[14:15]
	v_pk_add_f32 v[76:77], v[16:17], v[18:19]
	v_pk_add_f32 v[70:71], v[70:71], v[72:73]
	v_pk_add_f32 v[74:75], v[74:75], v[76:77]
	v_pk_add_f32 v[70:71], v[70:71], v[74:75]
	s_nop 0
	v_add_f32_e32 v70, v70, v71
	s_nop 1
	v_add_f32_dpp v70, v70, v70 quad_perm:[1,0,3,2] row_mask:0xf bank_mask:0xf bound_ctrl:1
	s_nop 1
	v_add_f32_dpp v70, v70, v70 quad_perm:[2,3,0,1] row_mask:0xf bank_mask:0xf bound_ctrl:1
	s_nop 1
	v_add_f32_dpp v70, v70, v70 row_half_mirror row_mask:0xf bank_mask:0xf bound_ctrl:1
	s_nop 1
	v_add_f32_dpp v70, v70, v70 row_mirror row_mask:0xf bank_mask:0xf bound_ctrl:1
	s_nop 1
	v_readlane_b32 s3, v70, 16
	v_readlane_b32 s9, v70, 48
	v_readlane_b32 s2, v70, 0
	v_readlane_b32 s8, v70, 32
	s_nop 1
	v_mov_b32_e32 v76, s3
	v_mov_b32_e32 v77, s9
	v_add_f32_e32 v76, s2, v76
	v_add_f32_e32 v77, s8, v77
	v_add_f32_e32 v70, v76, v77
	v_fmac_f32_e32 v4, 0xba800000, v70
	v_fmac_f32_e32 v5, 0xba800000, v70
	v_fmac_f32_e32 v6, 0xba800000, v70
	v_fmac_f32_e32 v7, 0xba800000, v70
	v_fmac_f32_e32 v8, 0xba800000, v70
	v_fmac_f32_e32 v9, 0xba800000, v70
	v_fmac_f32_e32 v10, 0xba800000, v70
	v_fmac_f32_e32 v11, 0xba800000, v70
	v_fmac_f32_e32 v12, 0xba800000, v70
	v_fmac_f32_e32 v13, 0xba800000, v70
	v_fmac_f32_e32 v14, 0xba800000, v70
	v_fmac_f32_e32 v15, 0xba800000, v70
	v_fmac_f32_e32 v16, 0xba800000, v70
	v_fmac_f32_e32 v17, 0xba800000, v70
	v_fmac_f32_e32 v18, 0xba800000, v70
	v_fmac_f32_e32 v19, 0xba800000, v70
	v_pk_mul_f32 v[72:73], v[4:5], v[4:5]
	v_pk_mul_f32 v[74:75], v[6:7], v[6:7]
	v_pk_fma_f32 v[72:73], v[8:9], v[8:9], v[72:73]
	v_pk_fma_f32 v[74:75], v[10:11], v[10:11], v[74:75]
	v_pk_fma_f32 v[72:73], v[12:13], v[12:13], v[72:73]
	v_pk_fma_f32 v[74:75], v[14:15], v[14:15], v[74:75]
	v_pk_fma_f32 v[72:73], v[16:17], v[16:17], v[72:73]
	v_pk_fma_f32 v[74:75], v[18:19], v[18:19], v[74:75]
	v_pk_add_f32 v[72:73], v[72:73], v[74:75]
	s_nop 0
	v_add_f32_e32 v71, v72, v73
	s_nop 1
	v_add_f32_dpp v71, v71, v71 quad_perm:[1,0,3,2] row_mask:0xf bank_mask:0xf bound_ctrl:1
	s_nop 1
	v_add_f32_dpp v71, v71, v71 quad_perm:[2,3,0,1] row_mask:0xf bank_mask:0xf bound_ctrl:1
	s_nop 1
	v_add_f32_dpp v71, v71, v71 row_half_mirror row_mask:0xf bank_mask:0xf bound_ctrl:1
	s_nop 1
	v_add_f32_dpp v71, v71, v71 row_mirror row_mask:0xf bank_mask:0xf bound_ctrl:1
	s_nop 1
	v_readlane_b32 s3, v71, 16
	v_readlane_b32 s9, v71, 48
	v_readlane_b32 s2, v71, 0
	v_readlane_b32 s8, v71, 32
	s_nop 1
	v_mov_b32_e32 v76, s3
	v_mov_b32_e32 v77, s9
	v_add_f32_e32 v76, s2, v76
	v_add_f32_e32 v77, s8, v77
	v_add_f32_e32 v71, v76, v77
	v_fmamk_f32 v71, v71, 0x3a800000, v164
	v_rsq_f32_e32 v72, v71
	s_nop 1
	v_pk_mul_f32 v[4:5], v[4:5], v[72:73] op_sel_hi:[1,0]
	v_pk_mul_f32 v[6:7], v[6:7], v[72:73] op_sel_hi:[1,0]
	v_pk_mul_f32 v[8:9], v[8:9], v[72:73] op_sel_hi:[1,0]
	v_pk_mul_f32 v[10:11], v[10:11], v[72:73] op_sel_hi:[1,0]
	v_pk_mul_f32 v[12:13], v[12:13], v[72:73] op_sel_hi:[1,0]
	v_pk_mul_f32 v[14:15], v[14:15], v[72:73] op_sel_hi:[1,0]
	v_pk_mul_f32 v[16:17], v[16:17], v[72:73] op_sel_hi:[1,0]
	v_pk_mul_f32 v[18:19], v[18:19], v[72:73] op_sel_hi:[1,0]
	v_pk_fma_f32 v[42:43], v[4:5], v[100:101], v[116:117]
	v_pk_fma_f32 v[44:45], v[6:7], v[102:103], v[118:119]
	v_pk_fma_f32 v[46:47], v[8:9], v[104:105], v[120:121]
	v_pk_fma_f32 v[48:49], v[10:11], v[106:107], v[122:123]
	v_pk_fma_f32 v[50:51], v[12:13], v[108:109], v[124:125]
	v_pk_fma_f32 v[52:53], v[14:15], v[110:111], v[126:127]
	v_pk_fma_f32 v[54:55], v[16:17], v[112:113], v[128:129]
	v_pk_fma_f32 v[56:57], v[18:19], v[114:115], v[130:131]
	s_lshl_b32 s12, s20, 1
	s_add_u32 s12, s13, s12
	s_lshl_b32 s90, s20, 13
	s_add_u32 s18, s10, s90
	s_addc_u32 s19, s11, 0
	s_cmp_lt_u32 s12, 0x8200
	s_cselect_b32 s18, s18, s10
	s_cselect_b32 s19, s19, s11
	global_load_dwordx4 v[4:7], v1, s[18:19]
	global_load_dwordx4 v[8:11], v1, s[18:19] offset:1024
	global_load_dwordx4 v[12:15], v1, s[18:19] offset:2048
	global_load_dwordx4 v[16:19], v1, s[18:19] offset:3072
	v_cvt_pk_bf16_f32 v58, v42, v43
	v_cvt_pk_bf16_f32 v59, v44, v45
	v_cvt_pk_bf16_f32 v60, v46, v47
	v_cvt_pk_bf16_f32 v61, v48, v49
	v_cvt_pk_bf16_f32 v62, v50, v51
	v_cvt_pk_bf16_f32 v63, v52, v53
	v_cvt_pk_bf16_f32 v64, v54, v55
	v_cvt_pk_bf16_f32 v65, v56, v57
	global_store_dwordx4 v1, v[42:45], s[10:11] sc1
	global_store_dwordx4 v1, v[46:49], s[10:11] offset:1024 sc1
	global_store_dwordx4 v1, v[50:53], s[10:11] offset:2048 sc1
	global_store_dwordx4 v1, v[54:57], s[10:11] offset:3072 sc1
	global_store_dwordx2 v2, v[58:59], s[14:15]
	global_store_dwordx2 v2, v[60:61], s[14:15] offset:512
	global_store_dwordx2 v2, v[62:63], s[14:15] offset:1024
	global_store_dwordx2 v2, v[64:65], s[14:15] offset:1536
	s_add_u32 s13, s13, s20
	s_lshl_b32 s90, s20, 12
	s_add_u32 s10, s10, s90
	s_addc_u32 s11, s11, 0
	s_lshl_b32 s90, s20, 11
	s_add_u32 s14, s14, s90
	s_addc_u32 s15, s15, 0
	s_branch .Lln10_loopB

; __device__ __forceinline__ unsigned pk2(float lo, float hi) { const f32x2_ v = {lo, hi}; return __builtin_bit_cast(unsigned, __builtin_convertvector(v, bf16x2_)); }
; __device__ __forceinline__ void cache_phase(const PP P, int l) {
;     ...
;     for (int g = P.bid * 512 + tid; g < 65536 * 32; g += G * 512) {
;         const int prow = g >> 5, c8 = g & 31, b = prow >> 11, s = prow & 2047;
;         const float* sp = cckv + (size_t)prow * 256 + c8 * 8; const f32x4 a = *(const f32x4*)sp, c = *(const f32x4*)(sp + 4);
;         u32x4 w; w.x = pk2(a[0], a[1]); w.y = pk2(a[2], a[3]); w.z = pk2(c[0], c[1]); w.w = pk2(c[2], c[3]);
;         *(u32x4*)(CKVB + ((size_t)MP + (size_t)b * 2048 + s) * 256 + c8 * 8) = w;
;     }
.Lcva_loop:
	v_mov_b32_e32 v110, v0
	v_add_u32_e32 v111, s12, v110
	v_add_u32_e32 v112, s12, v111
	v_add_u32_e32 v113, s12, v112
	v_add_u32_e32 v114, s12, v113
	v_add_u32_e32 v115, s12, v114
	v_add_u32_e32 v116, s12, v115
	v_add_u32_e32 v117, s12, v116
	v_min_u32_e32 v10, 0x1fffff, v110
	v_min_u32_e32 v11, 0x1fffff, v111
	v_min_u32_e32 v12, 0x1fffff, v112
	v_min_u32_e32 v13, 0x1fffff, v113
	v_min_u32_e32 v14, 0x1fffff, v114
	v_min_u32_e32 v15, 0x1fffff, v115
	v_min_u32_e32 v16, 0x1fffff, v116
	v_min_u32_e32 v17, 0x1fffff, v117
	v_lshlrev_b32_e32 v100, 5, v10
	v_lshlrev_b32_e32 v101, 5, v11
	v_lshlrev_b32_e32 v102, 5, v12
	v_lshlrev_b32_e32 v103, 5, v13
	v_lshlrev_b32_e32 v104, 5, v14
	v_lshlrev_b32_e32 v105, 5, v15
	v_lshlrev_b32_e32 v106, 5, v16
	v_lshlrev_b32_e32 v107, 5, v17
	global_load_dwordx4 v[30:33], v100, s[8:9]
	global_load_dwordx4 v[34:37], v100, s[8:9] offset:16
	global_load_dwordx4 v[38:41], v101, s[8:9]
	global_load_dwordx4 v[42:45], v101, s[8:9] offset:16
	global_load_dwordx4 v[46:49], v102, s[8:9]
	global_load_dwordx4 v[50:53], v102, s[8:9] offset:16
	global_load_dwordx4 v[54:57], v103, s[8:9]
	global_load_dwordx4 v[58:61], v103, s[8:9] offset:16
	global_load_dwordx4 v[62:65], v104, s[8:9]
	global_load_dwordx4 v[66:69], v104, s[8:9] offset:16
	global_load_dwordx4 v[70:73], v105, s[8:9]
	global_load_dwordx4 v[74:77], v105, s[8:9] offset:16
	global_load_dwordx4 v[78:81], v106, s[8:9]
	global_load_dwordx4 v[82:85], v106, s[8:9] offset:16
	global_load_dwordx4 v[86:89], v107, s[8:9]
	global_load_dwordx4 v[90:93], v107, s[8:9] offset:16
	v_lshlrev_b32_e32 v10, 4, v10
	v_lshlrev_b32_e32 v11, 4, v11
	v_lshlrev_b32_e32 v12, 4, v12
	v_lshlrev_b32_e32 v13, 4, v13
	v_lshlrev_b32_e32 v14, 4, v14
	v_lshlrev_b32_e32 v15, 4, v15
	v_lshlrev_b32_e32 v16, 4, v16
	v_lshlrev_b32_e32 v17, 4, v17
	v_add_u32_e32 v0, s13, v0
	s_waitcnt vmcnt(14)
	v_cvt_pk_bf16_f32 v30, v30, v31
	v_cvt_pk_bf16_f32 v31, v32, v33
	v_cvt_pk_bf16_f32 v32, v34, v35
	v_cvt_pk_bf16_f32 v33, v36, v37
	s_waitcnt vmcnt(12)
	v_cvt_pk_bf16_f32 v38, v38, v39
	v_cvt_pk_bf16_f32 v39, v40, v41
	v_cvt_pk_bf16_f32 v40, v42, v43
	v_cvt_pk_bf16_f32 v41, v44, v45
	s_waitcnt vmcnt(10)
	v_cvt_pk_bf16_f32 v46, v46, v47
	v_cvt_pk_bf16_f32 v47, v48, v49
	v_cvt_pk_bf16_f32 v48, v50, v51
	v_cvt_pk_bf16_f32 v49, v52, v53
	s_waitcnt vmcnt(8)
	v_cvt_pk_bf16_f32 v54, v54, v55
	v_cvt_pk_bf16_f32 v55, v56, v57
	v_cvt_pk_bf16_f32 v56, v58, v59
	v_cvt_pk_bf16_f32 v57, v60, v61
	s_waitcnt vmcnt(6)
	v_cvt_pk_bf16_f32 v62, v62, v63
	v_cvt_pk_bf16_f32 v63, v64, v65
	v_cvt_pk_bf16_f32 v64, v66, v67
	v_cvt_pk_bf16_f32 v65, v68, v69
	s_waitcnt vmcnt(4)
	v_cvt_pk_bf16_f32 v70, v70, v71
	v_cvt_pk_bf16_f32 v71, v72, v73
	v_cvt_pk_bf16_f32 v72, v74, v75
	v_cvt_pk_bf16_f32 v73, v76, v77
	s_waitcnt vmcnt(2)
	v_cvt_pk_bf16_f32 v78, v78, v79
	v_cvt_pk_bf16_f32 v79, v80, v81
	v_cvt_pk_bf16_f32 v80, v82, v83
	v_cvt_pk_bf16_f32 v81, v84, v85
	s_waitcnt vmcnt(0)
	v_cvt_pk_bf16_f32 v86, v86, v87
	v_cvt_pk_bf16_f32 v87, v88, v89
	v_cvt_pk_bf16_f32 v88, v90, v91
	v_cvt_pk_bf16_f32 v89, v92, v93
	global_store_dwordx4 v10, v[30:33], s[6:7] sc1
	v_cmp_gt_u32_e32 vcc, 0x200000, v111
	s_and_saveexec_b64 s[10:11], vcc
	global_store_dwordx4 v11, v[38:41], s[6:7] sc1
	s_mov_b64 exec, s[10:11]
	v_cmp_gt_u32_e32 vcc, 0x200000, v112
	s_and_saveexec_b64 s[10:11], vcc
	global_store_dwordx4 v12, v[46:49], s[6:7] sc1
	s_mov_b64 exec, s[10:11]
	v_cmp_gt_u32_e32 vcc, 0x200000, v113
	s_and_saveexec_b64 s[10:11], vcc
	global_store_dwordx4 v13, v[54:57], s[6:7] sc1
	s_mov_b64 exec, s[10:11]
	v_cmp_gt_u32_e32 vcc, 0x200000, v114
	s_and_saveexec_b64 s[10:11], vcc
	global_store_dwordx4 v14, v[62:65], s[6:7] sc1
	s_mov_b64 exec, s[10:11]
	v_cmp_gt_u32_e32 vcc, 0x200000, v115
	s_and_saveexec_b64 s[10:11], vcc
	global_store_dwordx4 v15, v[70:73], s[6:7] sc1
	s_mov_b64 exec, s[10:11]
	v_cmp_gt_u32_e32 vcc, 0x200000, v116
	s_and_saveexec_b64 s[10:11], vcc
	global_store_dwordx4 v16, v[78:81], s[6:7] sc1
	s_mov_b64 exec, s[10:11]
	v_cmp_gt_u32_e32 vcc, 0x200000, v117
	s_and_saveexec_b64 s[10:11], vcc
	global_store_dwordx4 v17, v[86:89], s[6:7] sc1
	s_mov_b64 exec, s[10:11]
	v_cmp_gt_u32_e32 vcc, 0x200000, v0
	s_and_b64 exec, exec, vcc
	s_cbranch_execnz .Lcva_loop

; __device__ __forceinline__ unsigned pk2(float lo, float hi) { const f32x2_ v = {lo, hi}; return __builtin_bit_cast(unsigned, __builtin_convertvector(v, bf16x2_)); }
; __device__ __forceinline__ void cache_phase(const PP P, int l) {
;     ...
;     for (int g = P.bid * 512 + tid; g < 65536 * 4; g += G * 512) {
;         const int prow = g >> 2, c8 = g & 3, b = prow >> 11, s = prow & 2047;
;         const float* sp = ckpe + (size_t)prow * 32 + c8 * 8; const f32x4 a = *(const f32x4*)sp, c = *(const f32x4*)(sp + 4);
;         u32x4 w; w.x = pk2(a[0], a[1]); w.y = pk2(a[2], a[3]); w.z = pk2(c[0], c[1]); w.w = pk2(c[2], c[3]);
;         *(u32x4*)(KPEB + ((size_t)MP + (size_t)b * 2048 + s) * 32 + c8 * 8) = w;
;     }
.Lcvb_loop:
	v_mov_b32_e32 v110, v0
	v_add_u32_e32 v111, s12, v110
	v_add_u32_e32 v112, s12, v111
	v_min_u32_e32 v10, 0x3ffff, v110
	v_min_u32_e32 v11, 0x3ffff, v111
	v_min_u32_e32 v12, 0x3ffff, v112
	v_lshlrev_b32_e32 v100, 5, v10
	v_lshlrev_b32_e32 v101, 5, v11
	v_lshlrev_b32_e32 v102, 5, v12
	global_load_dwordx4 v[30:33], v100, s[2:3]
	global_load_dwordx4 v[34:37], v100, s[2:3] offset:16
	global_load_dwordx4 v[38:41], v101, s[2:3]
	global_load_dwordx4 v[42:45], v101, s[2:3] offset:16
	global_load_dwordx4 v[46:49], v102, s[2:3]
	global_load_dwordx4 v[50:53], v102, s[2:3] offset:16
	v_lshlrev_b32_e32 v10, 4, v10
	v_lshlrev_b32_e32 v11, 4, v11
	v_lshlrev_b32_e32 v12, 4, v12
	v_add_u32_e32 v0, s13, v0
	s_waitcnt vmcnt(4)
	v_cvt_pk_bf16_f32 v30, v30, v31
	v_cvt_pk_bf16_f32 v31, v32, v33
	v_cvt_pk_bf16_f32 v32, v34, v35
	v_cvt_pk_bf16_f32 v33, v36, v37
	s_waitcnt vmcnt(2)
	v_cvt_pk_bf16_f32 v38, v38, v39
	v_cvt_pk_bf16_f32 v39, v40, v41
	v_cvt_pk_bf16_f32 v40, v42, v43
	v_cvt_pk_bf16_f32 v41, v44, v45
	s_waitcnt vmcnt(0)
	v_cvt_pk_bf16_f32 v46, v46, v47
	v_cvt_pk_bf16_f32 v47, v48, v49
	v_cvt_pk_bf16_f32 v48, v50, v51
	v_cvt_pk_bf16_f32 v49, v52, v53
	global_store_dwordx4 v10, v[30:33], s[6:7] sc1
	v_cmp_gt_u32_e32 vcc, 0x40000, v111
	s_and_saveexec_b64 s[10:11], vcc
	global_store_dwordx4 v11, v[38:41], s[6:7] sc1
	s_mov_b64 exec, s[10:11]
	v_cmp_gt_u32_e32 vcc, 0x40000, v112
	s_and_saveexec_b64 s[10:11], vcc
	global_store_dwordx4 v12, v[46:49], s[6:7] sc1
	s_mov_b64 exec, s[10:11]
	v_cmp_gt_u32_e32 vcc, 0x40000, v0
	s_and_b64 exec, exec, vcc
	s_cbranch_execnz .Lcvb_loop

; __device__ __forceinline__ void tok_phase(const PP P, int l) {
;     ...
;     for (int row = P.bid * 8 + wave; row < MT; row += G * 8) {
;         const bf16* hr = H + (size_t)row * HLD;
;         const bool smp = row >= MP; int b, t, pos;
;         if (!smp) { b = row >> 11; t = row & 2047; pos = t; } else { const int rr = row - MP; b = rr >> 4; t = rr & 15; pos = 2048 + t; }
;         const size_t krow = smp ? (size_t)MP + 65536 + (size_t)b * 16 + t : (size_t)row;
;         { float v[6]; float ss = 0.f;
; #pragma unroll
;           for (int i = 0; i < 3; ++i) { const unsigned w = *(const unsigned*)(hr + 128 * i + lane * 2); v[2 * i] = bf2f(w & 0xffffu); v[2 * i + 1] = bf2f(w >> 16); ss += v[2 * i] * v[2 * i] + v[2 * i + 1] * v[2 * i + 1]; }
;           ss = wave_sum(ss); const float rinv = __builtin_amdgcn_rsqf(ss * (1.0f / 384.0f) + 1e-6f);
; #pragma unroll
;           for (int i = 0; i < 3; ++i) { const int col = 128 * i + lane * 2; *(unsigned*)(CQN + (size_t)row * 384 + col) = pk2(v[2 * i] * rinv * qn[col], v[2 * i + 1] * rinv * qn[col + 1]); } }
;         { const u32x2 w = *(const u32x2*)(hr + C_CKV + lane * 4);
;           float v0 = bf2f(w.x & 0xffffu), v1 = bf2f(w.x >> 16), v2 = bf2f(w.y & 0xffffu), v3 = bf2f(w.y >> 16);
;           float ss = wave_sum(v0 * v0 + v1 * v1 + v2 * v2 + v3 * v3); const float rinv = __builtin_amdgcn_rsqf(ss * (1.0f / 256.0f) + 1e-6f);
;           const f32x4 gn = *(const f32x4*)(kvn + lane * 4);
;           f32x4 o; o[0] = v0 * rinv * gn[0]; o[1] = v1 * rinv * gn[1]; o[2] = v2 * rinv * gn[2]; o[3] = v3 * rinv * gn[3];
;           float* op = smp ? out + O_CKVS + ((size_t)(l * 32 + b) * 16 + t) * 256 : out + O_CKVP + ((size_t)(l * 16 + b) * 2048 + t) * 256;
;           *(f32x4*)(op + lane * 4) = o;
;           u32x2 pw; pw.x = pk2(o[0], o[1]); pw.y = pk2(o[2], o[3]); *(u32x2*)(CKVB + krow * 256 + lane * 4) = pw; }
;         if (lane < 16) { const float x1 = bf2f(hr[C_KPE + lane]), x2 = bf2f(hr[C_KPE + 16 + lane]); const float2 cs = rope[pos * 16 + lane];
;           const float o1 = x1 * cs.x - x2 * cs.y, o2 = x1 * cs.y + x2 * cs.x;
;           float* op = smp ? out + O_KPES + ((size_t)(l * 32 + b) * 16 + t) * 32 : out + O_KPEP + ((size_t)(l * 16 + b) * 2048 + t) * 32;
;           op[lane] = o1; op[16 + lane] = o2; KPEB[krow * 32 + lane] = (bf16)f2bf(o1); KPEB[krow * 32 + 16 + lane] = (bf16)f2bf(o2); }
.LBB0_469:
	v_ashrrev_i32_e32 v29, 31, v1
	v_cmp_lt_i32_e64 s[4:5], s93, v1
	v_cmp_gt_i32_e64 s[6:7], s33, v1
	s_and_saveexec_b64 s[8:9], s[6:7]
	s_xor_b64 s[8:9], exec, s[8:9]
	v_ashrrev_i32_e32 v16, 11, v1
	v_and_b32_e32 v28, 0x7ff, v1
	s_or_saveexec_b64 s[8:9], s[8:9]
	v_mov_b64_e32 v[20:21], 21
	v_mov_b64_e32 v[22:23], 0x8200000
	v_mov_b32_e32 v21, s16
	v_mov_b32_e32 v31, v28
	s_xor_b64 exec, exec, s[8:9]
	v_add_u32_e32 v15, 0xffff8000, v1
	v_and_b32_e32 v31, 15, v1
	v_mov_b64_e32 v[20:21], 14
	v_lshrrev_b32_e32 v16, 4, v15
	v_or_b32_e32 v28, 0x800, v31
	v_mov_b64_e32 v[22:23], 0xcd38000
	v_mov_b32_e32 v21, s17
	s_or_b64 exec, exec, s[8:9]
	v_mov_b64_e32 v[18:19], s[20:21]
	v_mad_i64_i32 v[18:19], s[8:9], v1, s99, v[18:19]
	v_mov_b32_e32 v15, v25
	v_lshl_add_u64 v[32:33], v[18:19], 0, v[14:15]
	global_load_dword v15, v[32:33], off
	global_load_dword v42, v[32:33], off offset:256
	global_load_dword v45, v[32:33], off offset:512
	s_nop 0
	global_load_dwordx2 v[32:33], v[8:9], off
	global_load_dwordx2 v[34:35], v[8:9], off offset:512
	global_load_dwordx2 v[36:37], v[8:9], off offset:1024
	v_lshl_add_u64 v[62:63], v[26:27], 1, v[18:19]
	v_mov_b32_e32 v66, v0
	v_mov_b32_e32 v67, v25
	v_lshl_or_b32 v68, v28, 4, v0
	v_mov_b32_e32 v69, v25
	global_load_dwordx2 v[52:53], v[62:63], off offset:768
	global_load_dwordx4 v[54:57], v[2:3], off
	v_lshl_add_u64 v[64:65], v[66:67], 1, v[18:19]
	v_lshl_add_u64 v[68:69], v[68:69], 3, s[10:11]
	global_load_ushort v58, v[64:65], off offset:1280
	global_load_ushort v59, v[64:65], off offset:1312
	global_load_dwordx2 v[60:61], v[68:69], off
	s_movk_i32 s8, 0x300
	v_mad_i64_i32 v[38:39], s[8:9], v1, s8, v[10:11]
	v_ashrrev_i32_e32 v17, 31, v16
	v_or_b32_e32 v24, 0x18000, v31
	s_waitcnt vmcnt(10)
	v_lshlrev_b32_e32 v40, 16, v15
	v_and_b32_e32 v41, 0xffff0000, v15
	s_waitcnt vmcnt(8)
	v_lshlrev_b32_e32 v44, 16, v45
	v_lshlrev_b32_e32 v43, 16, v42
	v_and_b32_e32 v42, 0xffff0000, v42
	v_and_b32_e32 v45, 0xffff0000, v45
	v_mov_b32_e32 v48, v40
	v_mov_b32_e32 v49, v44
	v_pk_mul_f32 v[46:47], v[42:43], v[42:43]
	v_mov_b32_e32 v50, v41
	v_mov_b32_e32 v51, v45
	v_pk_mul_f32 v[48:49], v[48:49], v[48:49]
	v_add_f32_e32 v15, v46, v47
	v_pk_fma_f32 v[46:47], v[50:51], v[50:51], v[48:49]
	v_lshl_add_u64 v[48:49], v[16:17], 4, v[24:25]
	v_add_f32_e32 v15, v46, v15
	v_add_f32_e32 v15, v15, v47
	v_lshlrev_b32_e32 v24, 1, v26
	v_lshl_add_u64 v[50:51], v[18:19], 0, v[24:25]
	v_add_f32_dpp v15, v15, v15 quad_perm:[1,0,3,2] row_mask:0xf bank_mask:0xf bound_ctrl:1
	s_nop 1
	v_add_f32_dpp v15, v15, v15 quad_perm:[2,3,0,1] row_mask:0xf bank_mask:0xf bound_ctrl:1
	s_nop 1
	v_add_f32_dpp v15, v15, v15 row_half_mirror row_mask:0xf bank_mask:0xf bound_ctrl:1
	s_nop 1
	v_add_f32_dpp v15, v15, v15 row_mirror row_mask:0xf bank_mask:0xf bound_ctrl:1
	s_nop 0
	v_readlane_b32 s14, v15, 16
	v_readlane_b32 s15, v15, 48
	v_readlane_b32 s8, v15, 0
	v_readlane_b32 s9, v15, 32
	v_mov_b32_e32 v46, s14
	v_mov_b32_e32 v47, s15
	v_pk_add_f32 v[46:47], s[8:9], v[46:47]
	s_nop 0
	v_add_f32_e32 v15, v46, v47
	v_fmamk_f32 v15, v15, 0x3b2aaaab, v165
	v_rsq_f32_e32 v46, v15
	s_nop 0
	v_pk_mul_f32 v[40:41], v[46:47], v[40:41] op_sel_hi:[0,1]
	v_pk_mul_f32 v[42:43], v[46:47], v[42:43] op_sel_hi:[0,1]
	v_pk_mul_f32 v[44:45], v[46:47], v[44:45] op_sel_hi:[0,1]
	s_waitcnt vmcnt(7)
	v_pk_mul_f32 v[32:33], v[32:33], v[40:41]
	s_waitcnt vmcnt(6)
	v_pk_mul_f32 v[34:35], v[34:35], v[42:43] op_sel:[0,1] op_sel_hi:[1,0]
	s_waitcnt vmcnt(5)
	v_pk_mul_f32 v[36:37], v[44:45], v[36:37]
	v_cvt_pk_bf16_f32 v15, v32, v33
	v_cvt_pk_bf16_f32 v17, v34, v35
	v_cvt_pk_bf16_f32 v24, v36, v37
	global_store_dword v[38:39], v15, off
	global_store_dword v[38:39], v17, off offset:256
	global_store_dword v[38:39], v24, off offset:512
	v_add_u32_e32 v40, v16, v21
	v_ashrrev_i32_e32 v41, 31, v40
	v_lshlrev_b64 v[20:21], v20, v[40:41]
	v_lshl_add_u64 v[38:39], s[62:63], 0, v[22:23]
	v_lshlrev_b32_e32 v24, 8, v31
	v_lshl_add_u64 v[20:21], v[38:39], 0, v[20:21]
	v_cndmask_b32_e64 v23, v29, v49, s[4:5]
	v_cndmask_b32_e64 v22, v1, v48, s[4:5]
	v_lshl_add_u64 v[20:21], v[24:25], 2, v[20:21]
	v_lshlrev_b32_e32 v24, 2, v26
	v_lshlrev_b64 v[38:39], 9, v[22:23]
	v_lshl_add_u64 v[20:21], v[20:21], 0, v[24:25]
	v_lshl_add_u64 v[38:39], v[4:5], 0, v[38:39]
	v_lshlrev_b32_e32 v24, 1, v0
	s_waitcnt vmcnt(7)
	v_lshlrev_b32_e32 v40, 16, v52
	v_and_b32_e32 v41, 0xffff0000, v52
	v_lshlrev_b32_e32 v36, 16, v53
	v_and_b32_e32 v37, 0xffff0000, v53
	v_pk_mul_f32 v[42:43], v[40:41], v[40:41]
	v_pk_mul_f32 v[44:45], v[36:37], v[36:37]
	v_add_f32_e32 v15, v42, v43
	v_add_f32_e32 v15, v44, v15
	v_add_f32_e32 v15, v45, v15
	s_nop 1
	v_add_f32_dpp v15, v15, v15 quad_perm:[1,0,3,2] row_mask:0xf bank_mask:0xf bound_ctrl:1
	s_nop 1
	v_add_f32_dpp v15, v15, v15 quad_perm:[2,3,0,1] row_mask:0xf bank_mask:0xf bound_ctrl:1
	s_nop 1
	v_add_f32_dpp v15, v15, v15 row_half_mirror row_mask:0xf bank_mask:0xf bound_ctrl:1
	s_nop 1
	v_add_f32_dpp v15, v15, v15 row_mirror row_mask:0xf bank_mask:0xf bound_ctrl:1
	s_nop 0
	v_readlane_b32 s14, v15, 16
	v_readlane_b32 s15, v15, 48
	v_readlane_b32 s8, v15, 0
	v_readlane_b32 s9, v15, 32
	v_mov_b32_e32 v42, s14
	v_mov_b32_e32 v43, s15
	v_pk_add_f32 v[42:43], s[8:9], v[42:43]
	s_nop 0
	v_add_f32_e32 v15, v42, v43
	v_fmamk_f32 v15, v15, 0x3b800000, v165
	v_rsq_f32_e32 v42, v15
	s_nop 0
	v_pk_mul_f32 v[40:41], v[42:43], v[40:41] op_sel_hi:[0,1]
	v_pk_mul_f32 v[36:37], v[42:43], v[36:37] op_sel_hi:[0,1]
	s_waitcnt vmcnt(6)
	v_pk_mul_f32 v[32:33], v[54:55], v[40:41]
	v_pk_mul_f32 v[34:35], v[56:57], v[36:37]
	global_store_dwordx4 v[20:21], v[32:35], off sc1
	v_cvt_pk_bf16_f32 v20, v32, v33
	v_cvt_pk_bf16_f32 v21, v34, v35
	global_store_dwordx2 v[38:39], v[20:21], off
	v_lshlrev_b32_e32 v20, 2, v0
	s_and_saveexec_b64 s[8:9], vcc
	s_cbranch_execz .LBB0_475
	v_mov_b32_e32 v36, s16
	v_mov_b32_e32 v37, s17
	v_cndmask_b32_e64 v36, v36, v37, s[4:5]
	v_add_u32_e32 v36, v16, v36
	v_cndmask_b32_e64 v34, v169, v170, s[4:5]
	v_mov_b32_e32 v35, v25
	v_cndmask_b32_e64 v38, 18, 11, s[4:5]
	v_ashrrev_i32_e32 v37, 31, v36
	v_lshl_add_u64 v[34:35], s[62:63], 0, v[34:35]
	v_lshlrev_b64 v[36:37], v38, v[36:37]
	v_lshlrev_b32_e32 v32, 5, v31
	v_mov_b32_e32 v33, v25
	v_lshl_add_u64 v[34:35], v[34:35], 0, v[36:37]
	v_mov_b32_e32 v21, v25
	v_lshl_add_u64 v[32:33], v[32:33], 2, v[34:35]
	v_lshl_add_u64 v[32:33], v[32:33], 0, v[20:21]
	v_lshlrev_b64 v[22:23], 6, v[22:23]
	v_lshl_add_u64 v[22:23], v[6:7], 0, v[22:23]
	s_waitcnt vmcnt(7)
	v_lshlrev_b32_e32 v15, 16, v58
	s_waitcnt vmcnt(6)
	v_lshlrev_b32_e32 v17, 16, v59
	s_waitcnt vmcnt(5)
	v_mul_f32_e32 v21, v61, v17
	v_mul_f32_e32 v17, v60, v17
	v_fma_f32 v21, v60, v15, -v21
	v_fmac_f32_e32 v17, v61, v15
	v_cvt_pk_bf16_f32 v15, v21, s0
	global_store_dword v[32:33], v21, off
	global_store_dword v[32:33], v17, off offset:64
	v_cvt_pk_bf16_f32 v17, v17, s0
	global_store_short v[22:23], v15, off
	global_store_short v[22:23], v17, off offset:32

; __device__ __forceinline__ unsigned pk2(float lo, float hi) { const f32x2_ v = {lo, hi}; return __builtin_bit_cast(unsigned, __builtin_convertvector(v, bf16x2_)); }
; __device__ __forceinline__ void prep_phase(const PP P, LAS unsigned char* lds, const int wl, const bool do_rest) {
;     ...
;     for (int g = P.bid * 512 + tid; g < MT * 128; g += G * 512) {
;         const int row = g >> 7, c8 = g & 127;
;         const float* s = (row < MP) ? KIN(0) + (size_t)row * 1024 + c8 * 8 : KIN(1) + (size_t)(row - MP) * 1024 + c8 * 8;
;         const f32x4 a = *(const f32x4*)s, b = *(const f32x4*)(s + 4);
;         u32x4 w; w.x = pk2(a[0], a[1]); w.y = pk2(a[2], a[3]); w.z = pk2(b[0], b[1]); w.w = pk2(b[2], b[3]);
;         *(u32x4*)(XB + (size_t)g * 8) = w;
;     }
.LBB0_747:
	s_or_b64 exec, exec, s[12:13]
	v_lshlrev_b64 v[4:5], 12, v[4:5]
	v_lshl_add_u64 v[4:5], v[6:7], 0, v[4:5]
	v_lshl_add_u64 v[10:11], v[4:5], 0, v[24:25]
	global_load_dwordx4 v[4:7], v[10:11], off
	s_nop 0
	global_load_dwordx4 v[10:13], v[10:11], off offset:16
	v_add_u32_e32 v8, s4, v8
	s_mov_b32 s5, 0x40ffff
	v_cmp_lt_i32_e32 vcc, s5, v8
	s_or_b64 s[8:9], vcc, s[8:9]
	s_waitcnt vmcnt(1)
	v_cvt_pk_bf16_f32 v4, v4, v5
	v_cvt_pk_bf16_f32 v5, v6, v7
	s_waitcnt vmcnt(0)
	v_cvt_pk_bf16_f32 v6, v10, v11
	v_cvt_pk_bf16_f32 v7, v12, v13
	global_store_dwordx4 v[2:3], v[4:7], off sc1
	v_lshl_add_u64 v[2:3], v[2:3], 0, s[6:7]
	s_andn2_b64 exec, exec, s[8:9]
	s_cbranch_execz .LBB0_752

;     __device__ __forceinline__ void operator()(const f32x4 (&acc)[2][2][4][2], const pg8::Unit& u, int wr, int wc, int fr, int fq) const {
;     ...
;             if (mode == 3) {
; #pragma unroll
;                 for (int ai = 0; ai < 2; ++ai)
; #pragma unroll
;                     for (int m = 0; m < 4; ++m) { const int row = row0 + ai * 128 + m * 16;
;                         const float* src = (row < MP) ? xp + (size_t)row * 1024 : xs + (size_t)(row - MP) * 1024;
;                         float* dst = X + (size_t)row * 1024;
; #pragma unroll
;                         for (int bj = 0; bj < 2; ++bj)
; #pragma unroll
;                             for (int n = 0; n < 2; ++n) { const int col = u.pn * 256 + bj * 128 + wc * 32 + n * 16 + 4 * fq;
;                                 const f32x4 xi = *(const f32x4*)(src + col); f32x4 o = xi * DN_ALPHA + acc[ai][bj][m][n];
;                                 *(f32x4*)(dst + col) = o; }
;                         __builtin_amdgcn_sched_barrier(0); }
.LBB0_854:
	s_and_b64 vcc, exec, s[6:7]
	s_cbranch_vccz .LBB0_853
	v_cmp_lt_i32_e32 vcc, s93, v142
	s_and_saveexec_b64 s[6:7], vcc
	s_xor_b64 s[6:7], exec, s[6:7]
	v_add_u32_e32 v24, 0xffff8000, v142
	v_lshlrev_b64 v[144:145], 12, v[24:25]
	v_mov_b32_e32 v143, v25
	v_lshl_add_u64 v[146:147], s[56:57], 0, v[144:145]
	v_lshlrev_b64 v[148:149], 12, v[142:143]
	s_andn2_saveexec_b64 s[6:7], s[6:7]
	v_ashrrev_i32_e32 v143, 31, v142
	v_lshlrev_b64 v[148:149], 12, v[142:143]
	v_lshl_add_u64 v[146:147], s[2:3], 0, v[148:149]
	s_or_b64 exec, exec, s[6:7]
	v_or_b32_e32 v144, s15, v186
	v_ashrrev_i32_e32 v145, 31, v144
	v_lshlrev_b64 v[144:145], 2, v[144:145]
	v_lshl_add_u64 v[146:147], v[146:147], 0, v[144:145]
	v_lshl_add_u64 v[148:149], s[62:63], 0, v[148:149]
	v_lshl_add_u64 v[148:149], v[148:149], 0, v[144:145]
	s_mov_b64 s[6:7], 0x10000
	s_mov_b64 vcc, 0x40000
	global_load_dwordx4 v[190:193], v[146:147], off
	global_load_dwordx4 v[194:197], v[146:147], off offset:64
	global_load_dwordx4 v[198:201], v[146:147], off offset:512
	global_load_dwordx4 v[202:205], v[146:147], off offset:576
	v_lshl_add_u64 v[146:147], v[146:147], 0, s[6:7]
	global_load_dwordx4 v[206:209], v[146:147], off
	global_load_dwordx4 v[210:213], v[146:147], off offset:64
	global_load_dwordx4 v[214:217], v[146:147], off offset:512
	global_load_dwordx4 v[218:221], v[146:147], off offset:576
	v_lshl_add_u64 v[146:147], v[146:147], 0, s[6:7]
	global_load_dwordx4 v[222:225], v[146:147], off
	global_load_dwordx4 v[226:229], v[146:147], off offset:64
	global_load_dwordx4 v[230:233], v[146:147], off offset:512
	global_load_dwordx4 v[234:237], v[146:147], off offset:576
	v_lshl_add_u64 v[146:147], v[146:147], 0, s[6:7]
	global_load_dwordx4 v[238:241], v[146:147], off
	global_load_dwordx4 v[242:245], v[146:147], off offset:64
	global_load_dwordx4 v[246:249], v[146:147], off offset:512
	global_load_dwordx4 v[250:253], v[146:147], off offset:576
	v_lshl_add_u64 v[146:147], v[146:147], 0, s[6:7]
	v_lshl_add_u64 v[146:147], v[146:147], 0, vcc
	s_waitcnt vmcnt(15)
	v_pk_fma_f32 v[126:127], v[190:191], s[86:87], v[126:127] op_sel_hi:[1,0,1]
	v_pk_fma_f32 v[128:129], v[192:193], s[86:87], v[128:129] op_sel_hi:[1,0,1]
	s_waitcnt vmcnt(14)
	v_pk_fma_f32 v[122:123], v[194:195], s[86:87], v[122:123] op_sel_hi:[1,0,1]
	v_pk_fma_f32 v[124:125], v[196:197], s[86:87], v[124:125] op_sel_hi:[1,0,1]
	s_waitcnt vmcnt(13)
	v_pk_fma_f32 v[118:119], v[198:199], s[86:87], v[118:119] op_sel_hi:[1,0,1]
	v_pk_fma_f32 v[120:121], v[200:201], s[86:87], v[120:121] op_sel_hi:[1,0,1]
	s_waitcnt vmcnt(12)
	v_pk_fma_f32 v[114:115], v[202:203], s[86:87], v[114:115] op_sel_hi:[1,0,1]
	v_pk_fma_f32 v[116:117], v[204:205], s[86:87], v[116:117] op_sel_hi:[1,0,1]
	global_store_dwordx4 v[148:149], v[126:129], off sc1
	global_store_dwordx4 v[148:149], v[122:125], off offset:64 sc1
	global_store_dwordx4 v[148:149], v[118:121], off offset:512 sc1
	global_store_dwordx4 v[148:149], v[114:117], off offset:576 sc1
	v_lshl_add_u64 v[148:149], v[148:149], 0, s[6:7]
	s_waitcnt vmcnt(15)
	v_pk_fma_f32 v[110:111], v[206:207], s[86:87], v[110:111] op_sel_hi:[1,0,1]
	v_pk_fma_f32 v[112:113], v[208:209], s[86:87], v[112:113] op_sel_hi:[1,0,1]
	s_waitcnt vmcnt(14)
	v_pk_fma_f32 v[106:107], v[210:211], s[86:87], v[106:107] op_sel_hi:[1,0,1]
	v_pk_fma_f32 v[108:109], v[212:213], s[86:87], v[108:109] op_sel_hi:[1,0,1]
	s_waitcnt vmcnt(13)
	v_pk_fma_f32 v[102:103], v[214:215], s[86:87], v[102:103] op_sel_hi:[1,0,1]
	v_pk_fma_f32 v[104:105], v[216:217], s[86:87], v[104:105] op_sel_hi:[1,0,1]
	s_waitcnt vmcnt(12)
	v_pk_fma_f32 v[98:99], v[218:219], s[86:87], v[98:99] op_sel_hi:[1,0,1]
	v_pk_fma_f32 v[100:101], v[220:221], s[86:87], v[100:101] op_sel_hi:[1,0,1]
	global_store_dwordx4 v[148:149], v[110:113], off sc1
	global_store_dwordx4 v[148:149], v[106:109], off offset:64 sc1
	global_store_dwordx4 v[148:149], v[102:105], off offset:512 sc1
	global_store_dwordx4 v[148:149], v[98:101], off offset:576 sc1
	v_lshl_add_u64 v[148:149], v[148:149], 0, s[6:7]
	s_waitcnt vmcnt(15)
	v_pk_fma_f32 v[94:95], v[222:223], s[86:87], v[94:95] op_sel_hi:[1,0,1]
	v_pk_fma_f32 v[96:97], v[224:225], s[86:87], v[96:97] op_sel_hi:[1,0,1]
	s_waitcnt vmcnt(14)
	v_pk_fma_f32 v[90:91], v[226:227], s[86:87], v[90:91] op_sel_hi:[1,0,1]
	v_pk_fma_f32 v[92:93], v[228:229], s[86:87], v[92:93] op_sel_hi:[1,0,1]
	s_waitcnt vmcnt(13)
	v_pk_fma_f32 v[86:87], v[230:231], s[86:87], v[86:87] op_sel_hi:[1,0,1]
	v_pk_fma_f32 v[88:89], v[232:233], s[86:87], v[88:89] op_sel_hi:[1,0,1]
	s_waitcnt vmcnt(12)
	v_pk_fma_f32 v[82:83], v[234:235], s[86:87], v[82:83] op_sel_hi:[1,0,1]
	v_pk_fma_f32 v[84:85], v[236:237], s[86:87], v[84:85] op_sel_hi:[1,0,1]
	global_store_dwordx4 v[148:149], v[94:97], off sc1
	global_store_dwordx4 v[148:149], v[90:93], off offset:64 sc1
	global_store_dwordx4 v[148:149], v[86:89], off offset:512 sc1
	global_store_dwordx4 v[148:149], v[82:85], off offset:576 sc1
	v_lshl_add_u64 v[148:149], v[148:149], 0, s[6:7]
	s_waitcnt vmcnt(15)
	v_pk_fma_f32 v[78:79], v[238:239], s[86:87], v[78:79] op_sel_hi:[1,0,1]
	v_pk_fma_f32 v[80:81], v[240:241], s[86:87], v[80:81] op_sel_hi:[1,0,1]
	s_waitcnt vmcnt(14)
	v_pk_fma_f32 v[74:75], v[242:243], s[86:87], v[74:75] op_sel_hi:[1,0,1]
	v_pk_fma_f32 v[76:77], v[244:245], s[86:87], v[76:77] op_sel_hi:[1,0,1]
	s_waitcnt vmcnt(13)
	v_pk_fma_f32 v[70:71], v[246:247], s[86:87], v[70:71] op_sel_hi:[1,0,1]
	v_pk_fma_f32 v[72:73], v[248:249], s[86:87], v[72:73] op_sel_hi:[1,0,1]
	s_waitcnt vmcnt(12)
;     __device__ __forceinline__ void operator()(const f32x4 (&acc)[2][2][4][2], const pg8::Unit& u, int wr, int wc, int fr, int fq) const {
;     ...
;             if (mode == 3) {
; #pragma unroll
;                 for (int ai = 0; ai < 2; ++ai)
; #pragma unroll
;                     for (int m = 0; m < 4; ++m) { const int row = row0 + ai * 128 + m * 16;
;                         const float* src = (row < MP) ? xp + (size_t)row * 1024 : xs + (size_t)(row - MP) * 1024;
;                         float* dst = X + (size_t)row * 1024;
; #pragma unroll
;                         for (int bj = 0; bj < 2; ++bj)
; #pragma unroll
;                             for (int n = 0; n < 2; ++n) { const int col = u.pn * 256 + bj * 128 + wc * 32 + n * 16 + 4 * fq;
;                                 const f32x4 xi = *(const f32x4*)(src + col); f32x4 o = xi * DN_ALPHA + acc[ai][bj][m][n];
;                                 *(f32x4*)(dst + col) = o; }
;                         __builtin_amdgcn_sched_barrier(0); }
	v_pk_fma_f32 v[66:67], v[250:251], s[86:87], v[66:67] op_sel_hi:[1,0,1]
	v_pk_fma_f32 v[68:69], v[252:253], s[86:87], v[68:69] op_sel_hi:[1,0,1]
	global_store_dwordx4 v[148:149], v[78:81], off sc1
	global_store_dwordx4 v[148:149], v[74:77], off offset:64 sc1
	global_store_dwordx4 v[148:149], v[70:73], off offset:512 sc1
	global_store_dwordx4 v[148:149], v[66:69], off offset:576 sc1
	v_lshl_add_u64 v[148:149], v[148:149], 0, s[6:7]
	v_lshl_add_u64 v[148:149], v[148:149], 0, vcc
	global_load_dwordx4 v[190:193], v[146:147], off
	global_load_dwordx4 v[194:197], v[146:147], off offset:64
	global_load_dwordx4 v[198:201], v[146:147], off offset:512
	global_load_dwordx4 v[202:205], v[146:147], off offset:576
	v_lshl_add_u64 v[146:147], v[146:147], 0, s[6:7]
	global_load_dwordx4 v[206:209], v[146:147], off
	global_load_dwordx4 v[210:213], v[146:147], off offset:64
	global_load_dwordx4 v[214:217], v[146:147], off offset:512
	global_load_dwordx4 v[218:221], v[146:147], off offset:576
	v_lshl_add_u64 v[146:147], v[146:147], 0, s[6:7]
	global_load_dwordx4 v[222:225], v[146:147], off
	global_load_dwordx4 v[226:229], v[146:147], off offset:64
	global_load_dwordx4 v[230:233], v[146:147], off offset:512
	global_load_dwordx4 v[234:237], v[146:147], off offset:576
	v_lshl_add_u64 v[146:147], v[146:147], 0, s[6:7]
	global_load_dwordx4 v[238:241], v[146:147], off
	global_load_dwordx4 v[242:245], v[146:147], off offset:64
	global_load_dwordx4 v[246:249], v[146:147], off offset:512
	global_load_dwordx4 v[250:253], v[146:147], off offset:576
	v_lshl_add_u64 v[146:147], v[146:147], 0, s[6:7]
	s_waitcnt vmcnt(15)
	v_pk_fma_f32 v[62:63], v[190:191], s[86:87], v[62:63] op_sel_hi:[1,0,1]
	v_pk_fma_f32 v[64:65], v[192:193], s[86:87], v[64:65] op_sel_hi:[1,0,1]
	s_waitcnt vmcnt(14)
	v_pk_fma_f32 v[58:59], v[194:195], s[86:87], v[58:59] op_sel_hi:[1,0,1]
	v_pk_fma_f32 v[60:61], v[196:197], s[86:87], v[60:61] op_sel_hi:[1,0,1]
	s_waitcnt vmcnt(13)
	v_pk_fma_f32 v[54:55], v[198:199], s[86:87], v[54:55] op_sel_hi:[1,0,1]
	v_pk_fma_f32 v[56:57], v[200:201], s[86:87], v[56:57] op_sel_hi:[1,0,1]
	s_waitcnt vmcnt(12)
	v_pk_fma_f32 v[50:51], v[202:203], s[86:87], v[50:51] op_sel_hi:[1,0,1]
	v_pk_fma_f32 v[52:53], v[204:205], s[86:87], v[52:53] op_sel_hi:[1,0,1]
	global_store_dwordx4 v[148:149], v[62:65], off sc1
	global_store_dwordx4 v[148:149], v[58:61], off offset:64 sc1
	global_store_dwordx4 v[148:149], v[54:57], off offset:512 sc1
	global_store_dwordx4 v[148:149], v[50:53], off offset:576 sc1
	v_lshl_add_u64 v[148:149], v[148:149], 0, s[6:7]
	s_waitcnt vmcnt(15)
	v_pk_fma_f32 v[46:47], v[206:207], s[86:87], v[46:47] op_sel_hi:[1,0,1]
	v_pk_fma_f32 v[48:49], v[208:209], s[86:87], v[48:49] op_sel_hi:[1,0,1]
	s_waitcnt vmcnt(14)
	v_pk_fma_f32 v[42:43], v[210:211], s[86:87], v[42:43] op_sel_hi:[1,0,1]
	v_pk_fma_f32 v[44:45], v[212:213], s[86:87], v[44:45] op_sel_hi:[1,0,1]
	s_waitcnt vmcnt(13)
	v_pk_fma_f32 v[38:39], v[214:215], s[86:87], v[38:39] op_sel_hi:[1,0,1]
	v_pk_fma_f32 v[40:41], v[216:217], s[86:87], v[40:41] op_sel_hi:[1,0,1]
	s_waitcnt vmcnt(12)
	v_pk_fma_f32 v[34:35], v[218:219], s[86:87], v[34:35] op_sel_hi:[1,0,1]
	v_pk_fma_f32 v[36:37], v[220:221], s[86:87], v[36:37] op_sel_hi:[1,0,1]
	global_store_dwordx4 v[148:149], v[46:49], off sc1
	global_store_dwordx4 v[148:149], v[42:45], off offset:64 sc1
	global_store_dwordx4 v[148:149], v[38:41], off offset:512 sc1
	global_store_dwordx4 v[148:149], v[34:37], off offset:576 sc1
	v_lshl_add_u64 v[148:149], v[148:149], 0, s[6:7]
	s_waitcnt vmcnt(15)
	v_pk_fma_f32 v[30:31], v[222:223], s[86:87], v[30:31] op_sel_hi:[1,0,1]
	v_pk_fma_f32 v[32:33], v[224:225], s[86:87], v[32:33] op_sel_hi:[1,0,1]
	s_waitcnt vmcnt(14)
	v_pk_fma_f32 v[26:27], v[226:227], s[86:87], v[26:27] op_sel_hi:[1,0,1]
	v_pk_fma_f32 v[28:29], v[228:229], s[86:87], v[28:29] op_sel_hi:[1,0,1]
	s_waitcnt vmcnt(13)
	v_pk_fma_f32 v[20:21], v[230:231], s[86:87], v[20:21] op_sel_hi:[1,0,1]
	v_pk_fma_f32 v[22:23], v[232:233], s[86:87], v[22:23] op_sel_hi:[1,0,1]
	s_waitcnt vmcnt(12)
	v_pk_fma_f32 v[16:17], v[234:235], s[86:87], v[16:17] op_sel_hi:[1,0,1]
	v_pk_fma_f32 v[18:19], v[236:237], s[86:87], v[18:19] op_sel_hi:[1,0,1]
	global_store_dwordx4 v[148:149], v[30:33], off sc1
	global_store_dwordx4 v[148:149], v[26:29], off offset:64 sc1
	global_store_dwordx4 v[148:149], v[20:23], off offset:512 sc1
	global_store_dwordx4 v[148:149], v[16:19], off offset:576 sc1
	v_lshl_add_u64 v[148:149], v[148:149], 0, s[6:7]
	s_waitcnt vmcnt(15)
	v_pk_fma_f32 v[12:13], v[238:239], s[86:87], v[12:13] op_sel_hi:[1,0,1]
	v_pk_fma_f32 v[14:15], v[240:241], s[86:87], v[14:15] op_sel_hi:[1,0,1]
	s_waitcnt vmcnt(14)
	v_pk_fma_f32 v[8:9], v[242:243], s[86:87], v[8:9] op_sel_hi:[1,0,1]
	v_pk_fma_f32 v[10:11], v[244:245], s[86:87], v[10:11] op_sel_hi:[1,0,1]
	s_waitcnt vmcnt(13)
	v_pk_fma_f32 v[4:5], v[246:247], s[86:87], v[4:5] op_sel_hi:[1,0,1]
	v_pk_fma_f32 v[6:7], v[248:249], s[86:87], v[6:7] op_sel_hi:[1,0,1]
	s_waitcnt vmcnt(12)
	v_pk_fma_f32 v[0:1], v[250:251], s[86:87], v[0:1] op_sel_hi:[1,0,1]
	v_pk_fma_f32 v[2:3], v[252:253], s[86:87], v[2:3] op_sel_hi:[1,0,1]
	global_store_dwordx4 v[148:149], v[12:15], off sc1
	global_store_dwordx4 v[148:149], v[8:11], off offset:64 sc1
	global_store_dwordx4 v[148:149], v[4:7], off offset:512 sc1
	global_store_dwordx4 v[148:149], v[0:3], off offset:576 sc1
	v_lshl_add_u64 v[148:149], v[148:149], 0, s[6:7]
	s_and_b64 vcc, exec, s[4:5]
	s_mov_b64 s[4:5], -1
	s_cbranch_vccnz .LBB0_804

; __device__ __forceinline__ unsigned pk2(float lo, float hi) { const f32x2_ v = {lo, hi}; return __builtin_bit_cast(unsigned, __builtin_convertvector(v, bf16x2_)); }
; __device__ __forceinline__ float siluf_(float x) { return x * sigmoidf_(x); }
;     __device__ __forceinline__ void operator()(const f32x4 (&acc)[2][2][4][2], const pg8::Unit& u, int wr, int wc, int fr, int fq) const {
;     ...
;                 const int col0 = u.pn * 128 + wc * 32 + 8 * fq;
; #pragma unroll
;                 for (int ai = 0; ai < 2; ++ai)
; #pragma unroll
;                     for (int m = 0; m < 4; ++m) { bf16* rowp = O + (size_t)(row0 + ai * 128 + m * 16) * ldc + col0;
;                         float f[8];
; #pragma unroll
;                         for (int n = 0; n < 2; ++n)
; #pragma unroll
;                             for (int j = 0; j < 4; ++j) { const float g = acc[ai][0][m][n][j], up = acc[ai][1][m][n][j]; f[n * 4 + j] = siluf_(g) * up; }
;                         u32x4 w; w.x = pk2(f[0], f[1]); w.y = pk2(f[2], f[3]); w.z = pk2(f[4], f[5]); w.w = pk2(f[6], f[7]);
;                         *(u32x4*)rowp = w; }
.LBB0_924:
	v_lshl_add_u32 v146, s67, 8, v148
	v_mad_i64_i32 v[144:145], s[34:35], s70, v146, 0
	v_lshl_add_u64 v[144:145], v[144:145], 1, s[76:77]
	s_mov_b64 s[34:35], -1
	s_and_b64 vcc, exec, s[8:9]
	v_or_b32_e32 v186, 16, v146
	v_or_b32_e32 v185, 32, v146
	v_or_b32_e32 v184, 48, v146
	v_add_u32_e32 v155, 0x80, v146
	v_add_u32_e32 v154, 0x90, v146
	v_add_u32_e32 v153, 0xa0, v146
	v_add_u32_e32 v152, 0xb0, v146
	s_cbranch_vccz .LBB0_927
	v_mul_f32_e32 v146, 0xbfb8aa3b, v126
	v_mul_f32_e32 v147, 0xbfb8aa3b, v127
	v_exp_f32_e32 v146, v146
	v_exp_f32_e32 v147, v147
	v_mul_f32_e32 v187, 0xbfb8aa3b, v128
	v_exp_f32_e32 v187, v187
	v_add_f32_e32 v146, 1.0, v146
	v_add_f32_e32 v147, 1.0, v147
	v_rcp_f32_e32 v146, v146
	v_rcp_f32_e32 v147, v147
	v_mul_f32_e32 v190, 0xbfb8aa3b, v129
	v_exp_f32_e32 v192, v190
	v_lshl_or_b32 v188, s64, 7, v150
	v_pk_mul_f32 v[146:147], v[126:127], v[146:147]
	v_ashrrev_i32_e32 v189, 31, v188
	v_pk_mul_f32 v[190:191], v[146:147], v[110:111]
	v_add_f32_e32 v146, 1.0, v187
	v_mul_f32_e32 v187, 0xbfb8aa3b, v122
	v_add_f32_e32 v147, 1.0, v192
	v_exp_f32_e32 v187, v187
	v_mul_f32_e32 v192, 0xbfb8aa3b, v123
	v_exp_f32_e32 v193, v192
	v_rcp_f32_e32 v146, v146
	v_add_f32_e32 v187, 1.0, v187
	v_rcp_f32_e32 v192, v187
	v_add_f32_e32 v187, 1.0, v193
	v_mul_f32_e32 v193, 0xbfb8aa3b, v124
	v_exp_f32_e32 v194, v193
	v_mul_f32_e32 v193, 0xbfb8aa3b, v125
	v_exp_f32_e32 v195, v193
	v_rcp_f32_e32 v147, v147
	v_rcp_f32_e32 v193, v187
	v_add_f32_e32 v187, 1.0, v194
	v_rcp_f32_e32 v194, v187
	v_add_f32_e32 v187, 1.0, v195
	v_rcp_f32_e32 v195, v187
	v_pk_mul_f32 v[146:147], v[128:129], v[146:147]
	v_mul_f32_e32 v187, 0xbfb8aa3b, v118
	v_pk_mul_f32 v[196:197], v[146:147], v[112:113]
	v_pk_mul_f32 v[146:147], v[122:123], v[192:193]
	v_exp_f32_e32 v187, v187
	v_pk_mul_f32 v[192:193], v[146:147], v[106:107]
	v_pk_mul_f32 v[146:147], v[124:125], v[194:195]
	v_add_f32_e32 v187, 1.0, v187
	v_pk_mul_f32 v[194:195], v[146:147], v[108:109]
	v_lshlrev_b64 v[146:147], 1, v[188:189]
	v_cvt_pk_bf16_f32 v188, v190, v191
	v_cvt_pk_bf16_f32 v190, v192, v193
	v_mul_f32_e32 v192, 0xbfb8aa3b, v119
	v_exp_f32_e32 v192, v192
	v_lshl_add_u64 v[198:199], v[144:145], 0, v[146:147]
	v_cvt_pk_bf16_f32 v189, v196, v197
	v_cvt_pk_bf16_f32 v191, v194, v195
	global_store_dwordx4 v[198:199], v[188:191], off sc1
	v_mul_f32_e32 v194, 0xbfb8aa3b, v115
	v_exp_f32_e32 v195, v194
	v_rcp_f32_e32 v188, v187
	v_add_f32_e32 v187, 1.0, v192
	v_rcp_f32_e32 v189, v187
	v_mul_f32_e32 v187, 0xbfb8aa3b, v120
	v_exp_f32_e32 v187, v187
	v_mul_f32_e32 v192, 0xbfb8aa3b, v121
	v_exp_f32_e32 v193, v192
	v_pk_mul_f32 v[188:189], v[118:119], v[188:189]
	v_add_f32_e32 v187, 1.0, v187
	v_rcp_f32_e32 v192, v187
	v_add_f32_e32 v187, 1.0, v193
	v_rcp_f32_e32 v193, v187
	v_mul_f32_e32 v187, 0xbfb8aa3b, v114
	v_exp_f32_e32 v187, v187
	v_pk_mul_f32 v[188:189], v[188:189], v[94:95]
	v_pk_mul_f32 v[192:193], v[120:121], v[192:193]
	v_cvt_pk_bf16_f32 v188, v188, v189
	v_add_f32_e32 v187, 1.0, v187
	v_rcp_f32_e32 v194, v187
	v_add_f32_e32 v187, 1.0, v195
	v_mul_f32_e32 v195, 0xbfb8aa3b, v116
	v_exp_f32_e32 v196, v195
	v_mul_f32_e32 v195, 0xbfb8aa3b, v117
	v_exp_f32_e32 v197, v195
	v_rcp_f32_e32 v195, v187
	v_add_f32_e32 v187, 1.0, v196
	v_rcp_f32_e32 v196, v187
	v_add_f32_e32 v187, 1.0, v197
	v_rcp_f32_e32 v197, v187
	v_pk_mul_f32 v[192:193], v[192:193], v[96:97]
	v_mul_f32_e32 v187, 0xbfb8aa3b, v102
	v_cvt_pk_bf16_f32 v189, v192, v193
	v_exp_f32_e32 v187, v187
	v_mul_f32_e32 v192, 0xbfb8aa3b, v103
	v_exp_f32_e32 v192, v192
	v_mad_i64_i32 v[190:191], s[34:35], s70, v186, 0
	v_pk_mul_f32 v[194:195], v[114:115], v[194:195]
	v_pk_mul_f32 v[196:197], v[116:117], v[196:197]
	v_lshl_add_u64 v[190:191], v[190:191], 1, s[76:77]
	v_pk_mul_f32 v[194:195], v[194:195], v[90:91]
	v_pk_mul_f32 v[196:197], v[196:197], v[92:93]
	v_lshl_add_u64 v[198:199], v[190:191], 0, v[146:147]
	v_cvt_pk_bf16_f32 v190, v194, v195
	v_cvt_pk_bf16_f32 v191, v196, v197
	v_add_f32_e32 v187, 1.0, v187
	global_store_dwordx4 v[198:199], v[188:191], off sc1
	v_mul_f32_e32 v194, 0xbfb8aa3b, v99
	v_exp_f32_e32 v195, v194
	v_rcp_f32_e32 v188, v187
	v_add_f32_e32 v187, 1.0, v192
	v_rcp_f32_e32 v189, v187
	v_mul_f32_e32 v187, 0xbfb8aa3b, v104
	v_exp_f32_e32 v187, v187
	v_mul_f32_e32 v192, 0xbfb8aa3b, v105
	v_exp_f32_e32 v193, v192
	v_pk_mul_f32 v[188:189], v[102:103], v[188:189]
	v_add_f32_e32 v187, 1.0, v187
	v_rcp_f32_e32 v192, v187
	v_add_f32_e32 v187, 1.0, v193
	v_rcp_f32_e32 v193, v187
	v_mul_f32_e32 v187, 0xbfb8aa3b, v98
	v_exp_f32_e32 v187, v187
	v_pk_mul_f32 v[188:189], v[188:189], v[78:79]
	v_pk_mul_f32 v[192:193], v[104:105], v[192:193]
	v_cvt_pk_bf16_f32 v188, v188, v189
	v_add_f32_e32 v187, 1.0, v187
	v_rcp_f32_e32 v194, v187
	v_add_f32_e32 v187, 1.0, v195
	v_mul_f32_e32 v195, 0xbfb8aa3b, v100
	v_exp_f32_e32 v196, v195
	v_mul_f32_e32 v195, 0xbfb8aa3b, v101
	v_exp_f32_e32 v197, v195
	v_rcp_f32_e32 v195, v187
	v_add_f32_e32 v187, 1.0, v196
	v_rcp_f32_e32 v196, v187
	v_add_f32_e32 v187, 1.0, v197
	v_rcp_f32_e32 v197, v187
	v_pk_mul_f32 v[192:193], v[192:193], v[80:81]
	v_mul_f32_e32 v187, 0xbfb8aa3b, v86
	v_cvt_pk_bf16_f32 v189, v192, v193
	v_exp_f32_e32 v187, v187
	v_mul_f32_e32 v192, 0xbfb8aa3b, v87
	v_exp_f32_e32 v192, v192
	v_mad_i64_i32 v[190:191], s[34:35], s70, v185, 0
	v_pk_mul_f32 v[194:195], v[98:99], v[194:195]
	v_pk_mul_f32 v[196:197], v[100:101], v[196:197]
	v_lshl_add_u64 v[190:191], v[190:191], 1, s[76:77]
	v_pk_mul_f32 v[194:195], v[194:195], v[74:75]
	v_pk_mul_f32 v[196:197], v[196:197], v[76:77]
	v_lshl_add_u64 v[198:199], v[190:191], 0, v[146:147]
	v_cvt_pk_bf16_f32 v190, v194, v195
	v_cvt_pk_bf16_f32 v191, v196, v197
; __device__ __forceinline__ unsigned pk2(float lo, float hi) { const f32x2_ v = {lo, hi}; return __builtin_bit_cast(unsigned, __builtin_convertvector(v, bf16x2_)); }
; __device__ __forceinline__ float siluf_(float x) { return x * sigmoidf_(x); }
;     __device__ __forceinline__ void operator()(const f32x4 (&acc)[2][2][4][2], const pg8::Unit& u, int wr, int wc, int fr, int fq) const {
;     ...
;                 const int col0 = u.pn * 128 + wc * 32 + 8 * fq;
; #pragma unroll
;                 for (int ai = 0; ai < 2; ++ai)
; #pragma unroll
;                     for (int m = 0; m < 4; ++m) { bf16* rowp = O + (size_t)(row0 + ai * 128 + m * 16) * ldc + col0;
;                         float f[8];
; #pragma unroll
;                         for (int n = 0; n < 2; ++n)
; #pragma unroll
;                             for (int j = 0; j < 4; ++j) { const float g = acc[ai][0][m][n][j], up = acc[ai][1][m][n][j]; f[n * 4 + j] = siluf_(g) * up; }
;                         u32x4 w; w.x = pk2(f[0], f[1]); w.y = pk2(f[2], f[3]); w.z = pk2(f[4], f[5]); w.w = pk2(f[6], f[7]);
;                         *(u32x4*)rowp = w; }
	v_add_f32_e32 v187, 1.0, v187
	global_store_dwordx4 v[198:199], v[188:191], off sc1
	v_mul_f32_e32 v194, 0xbfb8aa3b, v83
	v_exp_f32_e32 v195, v194
	v_rcp_f32_e32 v188, v187
	v_add_f32_e32 v187, 1.0, v192
	v_rcp_f32_e32 v189, v187
	v_mul_f32_e32 v187, 0xbfb8aa3b, v88
	v_exp_f32_e32 v187, v187
	v_mul_f32_e32 v192, 0xbfb8aa3b, v89
	v_exp_f32_e32 v193, v192
	v_pk_mul_f32 v[188:189], v[86:87], v[188:189]
	v_add_f32_e32 v187, 1.0, v187
	v_rcp_f32_e32 v192, v187
	v_add_f32_e32 v187, 1.0, v193
	v_rcp_f32_e32 v193, v187
	v_mul_f32_e32 v187, 0xbfb8aa3b, v82
	v_exp_f32_e32 v187, v187
	v_pk_mul_f32 v[188:189], v[188:189], v[70:71]
	v_pk_mul_f32 v[192:193], v[88:89], v[192:193]
	v_cvt_pk_bf16_f32 v188, v188, v189
	v_add_f32_e32 v187, 1.0, v187
	v_rcp_f32_e32 v194, v187
	v_add_f32_e32 v187, 1.0, v195
	v_mul_f32_e32 v195, 0xbfb8aa3b, v84
	v_exp_f32_e32 v196, v195
	v_mul_f32_e32 v195, 0xbfb8aa3b, v85
	v_exp_f32_e32 v197, v195
	v_rcp_f32_e32 v195, v187
	v_add_f32_e32 v187, 1.0, v196
	v_rcp_f32_e32 v196, v187
	v_add_f32_e32 v187, 1.0, v197
	v_rcp_f32_e32 v197, v187
	v_pk_mul_f32 v[192:193], v[192:193], v[72:73]
	v_mul_f32_e32 v187, 0xbfb8aa3b, v62
	v_cvt_pk_bf16_f32 v189, v192, v193
	v_exp_f32_e32 v187, v187
	v_mul_f32_e32 v192, 0xbfb8aa3b, v63
	v_exp_f32_e32 v192, v192
	v_mad_i64_i32 v[190:191], s[34:35], s70, v184, 0
	v_pk_mul_f32 v[194:195], v[82:83], v[194:195]
	v_pk_mul_f32 v[196:197], v[84:85], v[196:197]
	v_lshl_add_u64 v[190:191], v[190:191], 1, s[76:77]
	v_pk_mul_f32 v[194:195], v[194:195], v[66:67]
	v_pk_mul_f32 v[196:197], v[196:197], v[68:69]
	v_lshl_add_u64 v[198:199], v[190:191], 0, v[146:147]
	v_cvt_pk_bf16_f32 v190, v194, v195
	v_cvt_pk_bf16_f32 v191, v196, v197
	v_add_f32_e32 v187, 1.0, v187
	global_store_dwordx4 v[198:199], v[188:191], off sc1
	v_mul_f32_e32 v194, 0xbfb8aa3b, v59
	v_exp_f32_e32 v195, v194
	v_rcp_f32_e32 v188, v187
	v_add_f32_e32 v187, 1.0, v192
	v_rcp_f32_e32 v189, v187
	v_mul_f32_e32 v187, 0xbfb8aa3b, v64
	v_exp_f32_e32 v187, v187
	v_mul_f32_e32 v192, 0xbfb8aa3b, v65
	v_exp_f32_e32 v193, v192
	v_pk_mul_f32 v[188:189], v[62:63], v[188:189]
	v_add_f32_e32 v187, 1.0, v187
	v_rcp_f32_e32 v192, v187
	v_add_f32_e32 v187, 1.0, v193
	v_rcp_f32_e32 v193, v187
	v_mul_f32_e32 v187, 0xbfb8aa3b, v58
	v_exp_f32_e32 v187, v187
	v_pk_mul_f32 v[188:189], v[188:189], v[46:47]
	v_pk_mul_f32 v[192:193], v[64:65], v[192:193]
	v_cvt_pk_bf16_f32 v188, v188, v189
	v_add_f32_e32 v187, 1.0, v187
	v_rcp_f32_e32 v194, v187
	v_add_f32_e32 v187, 1.0, v195
	v_mul_f32_e32 v195, 0xbfb8aa3b, v60
	v_exp_f32_e32 v196, v195
	v_mul_f32_e32 v195, 0xbfb8aa3b, v61
	v_exp_f32_e32 v197, v195
	v_rcp_f32_e32 v195, v187
	v_add_f32_e32 v187, 1.0, v196
	v_rcp_f32_e32 v196, v187
	v_add_f32_e32 v187, 1.0, v197
	v_rcp_f32_e32 v197, v187
	v_pk_mul_f32 v[192:193], v[192:193], v[48:49]
	v_mul_f32_e32 v187, 0xbfb8aa3b, v54
	v_cvt_pk_bf16_f32 v189, v192, v193
	v_exp_f32_e32 v187, v187
	v_mul_f32_e32 v192, 0xbfb8aa3b, v55
	v_exp_f32_e32 v192, v192
	v_mad_i64_i32 v[190:191], s[34:35], s70, v155, 0
	v_pk_mul_f32 v[194:195], v[58:59], v[194:195]
	v_pk_mul_f32 v[196:197], v[60:61], v[196:197]
	v_lshl_add_u64 v[190:191], v[190:191], 1, s[76:77]
	v_pk_mul_f32 v[194:195], v[194:195], v[42:43]
	v_pk_mul_f32 v[196:197], v[196:197], v[44:45]
	v_lshl_add_u64 v[198:199], v[190:191], 0, v[146:147]
	v_cvt_pk_bf16_f32 v190, v194, v195
	v_cvt_pk_bf16_f32 v191, v196, v197
	v_add_f32_e32 v187, 1.0, v187
	global_store_dwordx4 v[198:199], v[188:191], off sc1
	v_mul_f32_e32 v194, 0xbfb8aa3b, v51
	v_exp_f32_e32 v195, v194
	v_rcp_f32_e32 v188, v187
	v_add_f32_e32 v187, 1.0, v192
	v_rcp_f32_e32 v189, v187
	v_mul_f32_e32 v187, 0xbfb8aa3b, v56
	v_exp_f32_e32 v187, v187
	v_mul_f32_e32 v192, 0xbfb8aa3b, v57
	v_exp_f32_e32 v193, v192
	v_pk_mul_f32 v[188:189], v[54:55], v[188:189]
	v_add_f32_e32 v187, 1.0, v187
	v_rcp_f32_e32 v192, v187
	v_add_f32_e32 v187, 1.0, v193
	v_rcp_f32_e32 v193, v187
	v_mul_f32_e32 v187, 0xbfb8aa3b, v50
	v_exp_f32_e32 v187, v187
	v_pk_mul_f32 v[188:189], v[188:189], v[30:31]
	v_pk_mul_f32 v[192:193], v[56:57], v[192:193]
	v_cvt_pk_bf16_f32 v188, v188, v189
	v_add_f32_e32 v187, 1.0, v187
	v_rcp_f32_e32 v194, v187
	v_add_f32_e32 v187, 1.0, v195
; __device__ __forceinline__ unsigned pk2(float lo, float hi) { const f32x2_ v = {lo, hi}; return __builtin_bit_cast(unsigned, __builtin_convertvector(v, bf16x2_)); }
; __device__ __forceinline__ float siluf_(float x) { return x * sigmoidf_(x); }
;     __device__ __forceinline__ void operator()(const f32x4 (&acc)[2][2][4][2], const pg8::Unit& u, int wr, int wc, int fr, int fq) const {
;     ...
;                 const int col0 = u.pn * 128 + wc * 32 + 8 * fq;
; #pragma unroll
;                 for (int ai = 0; ai < 2; ++ai)
; #pragma unroll
;                     for (int m = 0; m < 4; ++m) { bf16* rowp = O + (size_t)(row0 + ai * 128 + m * 16) * ldc + col0;
;                         float f[8];
; #pragma unroll
;                         for (int n = 0; n < 2; ++n)
; #pragma unroll
;                             for (int j = 0; j < 4; ++j) { const float g = acc[ai][0][m][n][j], up = acc[ai][1][m][n][j]; f[n * 4 + j] = siluf_(g) * up; }
;                         u32x4 w; w.x = pk2(f[0], f[1]); w.y = pk2(f[2], f[3]); w.z = pk2(f[4], f[5]); w.w = pk2(f[6], f[7]);
;                         *(u32x4*)rowp = w; }
	v_mul_f32_e32 v195, 0xbfb8aa3b, v52
	v_exp_f32_e32 v196, v195
	v_mul_f32_e32 v195, 0xbfb8aa3b, v53
	v_exp_f32_e32 v197, v195
	v_rcp_f32_e32 v195, v187
	v_add_f32_e32 v187, 1.0, v196
	v_rcp_f32_e32 v196, v187
	v_add_f32_e32 v187, 1.0, v197
	v_rcp_f32_e32 v197, v187
	v_pk_mul_f32 v[192:193], v[192:193], v[32:33]
	v_mul_f32_e32 v187, 0xbfb8aa3b, v38
	v_cvt_pk_bf16_f32 v189, v192, v193
	v_exp_f32_e32 v187, v187
	v_mul_f32_e32 v192, 0xbfb8aa3b, v39
	v_exp_f32_e32 v192, v192
	v_mad_i64_i32 v[190:191], s[34:35], s70, v154, 0
	v_pk_mul_f32 v[194:195], v[50:51], v[194:195]
	v_pk_mul_f32 v[196:197], v[52:53], v[196:197]
	v_lshl_add_u64 v[190:191], v[190:191], 1, s[76:77]
	v_pk_mul_f32 v[194:195], v[194:195], v[26:27]
	v_pk_mul_f32 v[196:197], v[196:197], v[28:29]
	v_lshl_add_u64 v[198:199], v[190:191], 0, v[146:147]
	v_cvt_pk_bf16_f32 v190, v194, v195
	v_cvt_pk_bf16_f32 v191, v196, v197
	v_add_f32_e32 v187, 1.0, v187
	global_store_dwordx4 v[198:199], v[188:191], off sc1
	v_mul_f32_e32 v194, 0xbfb8aa3b, v35
	v_exp_f32_e32 v195, v194
	v_rcp_f32_e32 v188, v187
	v_add_f32_e32 v187, 1.0, v192
	v_rcp_f32_e32 v189, v187
	v_mul_f32_e32 v187, 0xbfb8aa3b, v40
	v_exp_f32_e32 v187, v187
	v_mul_f32_e32 v192, 0xbfb8aa3b, v41
	v_exp_f32_e32 v193, v192
	v_pk_mul_f32 v[188:189], v[38:39], v[188:189]
	v_add_f32_e32 v187, 1.0, v187
	v_rcp_f32_e32 v192, v187
	v_add_f32_e32 v187, 1.0, v193
	v_rcp_f32_e32 v193, v187
	v_mul_f32_e32 v187, 0xbfb8aa3b, v34
	v_exp_f32_e32 v187, v187
	v_pk_mul_f32 v[188:189], v[188:189], v[12:13]
	v_pk_mul_f32 v[192:193], v[40:41], v[192:193]
	v_cvt_pk_bf16_f32 v188, v188, v189
	v_add_f32_e32 v187, 1.0, v187
	v_rcp_f32_e32 v194, v187
	v_add_f32_e32 v187, 1.0, v195
	v_mul_f32_e32 v195, 0xbfb8aa3b, v36
	v_exp_f32_e32 v196, v195
	v_mul_f32_e32 v195, 0xbfb8aa3b, v37
	v_exp_f32_e32 v197, v195
	v_rcp_f32_e32 v195, v187
	v_add_f32_e32 v187, 1.0, v196
	v_rcp_f32_e32 v196, v187
	v_add_f32_e32 v187, 1.0, v197
	v_rcp_f32_e32 v197, v187
	v_pk_mul_f32 v[192:193], v[192:193], v[14:15]
	v_mul_f32_e32 v187, 0xbfb8aa3b, v20
	v_cvt_pk_bf16_f32 v189, v192, v193
	v_exp_f32_e32 v187, v187
	v_mul_f32_e32 v192, 0xbfb8aa3b, v21
	v_exp_f32_e32 v192, v192
	v_mad_i64_i32 v[190:191], s[34:35], s70, v153, 0
	v_pk_mul_f32 v[194:195], v[34:35], v[194:195]
	v_pk_mul_f32 v[196:197], v[36:37], v[196:197]
	v_lshl_add_u64 v[190:191], v[190:191], 1, s[76:77]
	v_pk_mul_f32 v[194:195], v[194:195], v[8:9]
	v_pk_mul_f32 v[196:197], v[196:197], v[10:11]
	v_lshl_add_u64 v[198:199], v[190:191], 0, v[146:147]
	v_cvt_pk_bf16_f32 v190, v194, v195
	v_cvt_pk_bf16_f32 v191, v196, v197
	v_add_f32_e32 v187, 1.0, v187
	global_store_dwordx4 v[198:199], v[188:191], off sc1
	v_mul_f32_e32 v194, 0xbfb8aa3b, v17
	v_exp_f32_e32 v195, v194
	v_rcp_f32_e32 v188, v187
	v_add_f32_e32 v187, 1.0, v192
	v_rcp_f32_e32 v189, v187
	v_mul_f32_e32 v187, 0xbfb8aa3b, v22
	v_exp_f32_e32 v187, v187
	v_mul_f32_e32 v192, 0xbfb8aa3b, v23
	v_exp_f32_e32 v193, v192
	v_mad_i64_i32 v[190:191], s[34:35], s70, v152, 0
	v_add_f32_e32 v187, 1.0, v187
	v_rcp_f32_e32 v192, v187
	v_add_f32_e32 v187, 1.0, v193
	v_rcp_f32_e32 v193, v187
	v_mul_f32_e32 v187, 0xbfb8aa3b, v16
	v_exp_f32_e32 v187, v187
	v_pk_mul_f32 v[188:189], v[20:21], v[188:189]
	v_pk_mul_f32 v[192:193], v[22:23], v[192:193]
	v_lshl_add_u64 v[190:191], v[190:191], 1, s[76:77]
	v_add_f32_e32 v187, 1.0, v187
	v_rcp_f32_e32 v194, v187
	v_add_f32_e32 v187, 1.0, v195
	v_mul_f32_e32 v195, 0xbfb8aa3b, v18
	v_exp_f32_e32 v196, v195
	v_mul_f32_e32 v195, 0xbfb8aa3b, v19
	v_exp_f32_e32 v197, v195
	v_rcp_f32_e32 v195, v187
	v_add_f32_e32 v187, 1.0, v196
	v_rcp_f32_e32 v196, v187
	v_add_f32_e32 v187, 1.0, v197
	v_rcp_f32_e32 v197, v187
	v_pk_mul_f32 v[194:195], v[16:17], v[194:195]
	v_pk_mul_f32 v[188:189], v[188:189], v[4:5]
	v_pk_mul_f32 v[192:193], v[192:193], v[6:7]
	v_pk_mul_f32 v[196:197], v[18:19], v[196:197]
	v_pk_mul_f32 v[194:195], v[194:195], v[0:1]
	v_pk_mul_f32 v[196:197], v[196:197], v[2:3]
	v_lshl_add_u64 v[146:147], v[190:191], 0, v[146:147]
	v_cvt_pk_bf16_f32 v188, v188, v189
	v_cvt_pk_bf16_f32 v189, v192, v193
	v_cvt_pk_bf16_f32 v190, v194, v195
	v_cvt_pk_bf16_f32 v191, v196, v197
	global_store_dwordx4 v[146:147], v[188:191], off sc1
	s_cbranch_execz .LBB0_928

; __device__ __forceinline__ unsigned pk2(float lo, float hi) { const f32x2_ v = {lo, hi}; return __builtin_bit_cast(unsigned, __builtin_convertvector(v, bf16x2_)); }
;     __device__ __forceinline__ void operator()(const f32x4 (&acc)[2][2][4][2], const pg8::Unit& u, int wr, int wc, int fr, int fq) const {
;     ...
;             if (mode == 0) {
;                 const int col0 = u.pn * 256 + wc * 32 + 8 * fq;
; #pragma unroll
;                 for (int ai = 0; ai < 2; ++ai)
; #pragma unroll
;                     for (int m = 0; m < 4; ++m) { bf16* rowp = O + (size_t)(row0 + ai * 128 + m * 16) * ldc + col0;
; #pragma unroll
;                         for (int bj = 0; bj < 2; ++bj) { const f32x4 v0 = acc[ai][bj][m][0], v1 = acc[ai][bj][m][1]; u32x4 w;
;                             w.x = pk2(v0[0], v0[1]); w.y = pk2(v0[2], v0[3]); w.z = pk2(v1[0], v1[1]); w.w = pk2(v1[2], v1[3]);
;                             *(u32x4*)(rowp + bj * 128) = w; } }
.LBB0_928:
	v_lshl_or_b32 v146, s64, 8, v150
	v_ashrrev_i32_e32 v147, 31, v146
	v_lshlrev_b64 v[146:147], 1, v[146:147]
	v_cvt_pk_bf16_f32 v110, v110, v111
	v_cvt_pk_bf16_f32 v111, v112, v113
	v_cvt_pk_bf16_f32 v112, v106, v107
	v_mad_i64_i32 v[106:107], s[34:35], s70, v186, 0
	v_lshl_add_u64 v[144:145], v[144:145], 0, v[146:147]
	v_cvt_pk_bf16_f32 v113, v108, v109
	v_lshl_add_u64 v[106:107], v[106:107], 1, s[76:77]
	v_cvt_pk_bf16_f32 v94, v94, v95
	v_cvt_pk_bf16_f32 v95, v96, v97
	v_cvt_pk_bf16_f32 v96, v90, v91
	v_mad_i64_i32 v[90:91], s[34:35], s70, v185, 0
	v_cvt_pk_bf16_f32 v126, v126, v127
	v_cvt_pk_bf16_f32 v127, v128, v129
	v_cvt_pk_bf16_f32 v128, v122, v123
	v_cvt_pk_bf16_f32 v129, v124, v125
	global_store_dwordx4 v[144:145], v[110:113], off offset:256 sc1
	v_cvt_pk_bf16_f32 v97, v92, v93
	v_lshl_add_u64 v[90:91], v[90:91], 1, s[76:77]
	v_lshl_add_u64 v[110:111], v[106:107], 0, v[146:147]
	v_cvt_pk_bf16_f32 v78, v78, v79
	v_cvt_pk_bf16_f32 v79, v80, v81
	v_cvt_pk_bf16_f32 v80, v74, v75
	v_mad_i64_i32 v[74:75], s[34:35], s70, v184, 0
	v_cvt_pk_bf16_f32 v70, v70, v71
	v_cvt_pk_bf16_f32 v71, v72, v73
	v_cvt_pk_bf16_f32 v72, v66, v67
	v_mad_i64_i32 v[66:67], s[34:35], s70, v155, 0
	global_store_dwordx4 v[144:145], v[126:129], off sc1
	v_cvt_pk_bf16_f32 v106, v118, v119
	v_cvt_pk_bf16_f32 v107, v120, v121
	v_cvt_pk_bf16_f32 v108, v114, v115
	v_cvt_pk_bf16_f32 v109, v116, v117
	global_store_dwordx4 v[110:111], v[94:97], off offset:256 sc1
	v_cvt_pk_bf16_f32 v81, v76, v77
	v_lshl_add_u64 v[74:75], v[74:75], 1, s[76:77]
	v_lshl_add_u64 v[94:95], v[90:91], 0, v[146:147]
	v_lshl_add_u64 v[66:67], v[66:67], 1, s[76:77]
	v_cvt_pk_bf16_f32 v46, v46, v47
	v_cvt_pk_bf16_f32 v47, v48, v49
	v_cvt_pk_bf16_f32 v48, v42, v43
	v_mad_i64_i32 v[42:43], s[34:35], s70, v154, 0
	global_store_dwordx4 v[110:111], v[106:109], off sc1
	v_cvt_pk_bf16_f32 v90, v102, v103
	v_cvt_pk_bf16_f32 v91, v104, v105
	v_cvt_pk_bf16_f32 v92, v98, v99
	v_cvt_pk_bf16_f32 v93, v100, v101
	global_store_dwordx4 v[94:95], v[78:81], off offset:256 sc1
	v_cvt_pk_bf16_f32 v76, v82, v83
	v_cvt_pk_bf16_f32 v77, v84, v85
	v_lshl_add_u64 v[78:79], v[74:75], 0, v[146:147]
	v_cvt_pk_bf16_f32 v74, v86, v87
	v_cvt_pk_bf16_f32 v75, v88, v89
	v_cvt_pk_bf16_f32 v73, v68, v69
	v_lshl_add_u64 v[66:67], v[66:67], 0, v[146:147]
	v_cvt_pk_bf16_f32 v49, v44, v45
	v_lshl_add_u64 v[42:43], v[42:43], 1, s[76:77]
	v_cvt_pk_bf16_f32 v30, v30, v31
	v_cvt_pk_bf16_f32 v31, v32, v33
	v_cvt_pk_bf16_f32 v32, v26, v27
	v_mad_i64_i32 v[26:27], s[34:35], s70, v153, 0
	global_store_dwordx4 v[94:95], v[90:93], off sc1
	global_store_dwordx4 v[78:79], v[74:77], off sc1
	global_store_dwordx4 v[78:79], v[70:73], off offset:256 sc1
	v_cvt_pk_bf16_f32 v62, v62, v63
	v_cvt_pk_bf16_f32 v63, v64, v65
	v_cvt_pk_bf16_f32 v64, v58, v59
	v_cvt_pk_bf16_f32 v65, v60, v61
	global_store_dwordx4 v[66:67], v[46:49], off offset:256 sc1
	v_cvt_pk_bf16_f32 v33, v28, v29
	v_lshl_add_u64 v[26:27], v[26:27], 1, s[76:77]
	v_lshl_add_u64 v[46:47], v[42:43], 0, v[146:147]
	v_cvt_pk_bf16_f32 v12, v12, v13
	v_cvt_pk_bf16_f32 v13, v14, v15
	v_cvt_pk_bf16_f32 v14, v8, v9
	v_mad_i64_i32 v[8:9], s[34:35], s70, v152, 0
	global_store_dwordx4 v[66:67], v[62:65], off sc1
	v_cvt_pk_bf16_f32 v42, v54, v55
	v_cvt_pk_bf16_f32 v43, v56, v57
	v_cvt_pk_bf16_f32 v44, v50, v51
	v_cvt_pk_bf16_f32 v45, v52, v53
	global_store_dwordx4 v[46:47], v[30:33], off offset:256 sc1
	v_cvt_pk_bf16_f32 v15, v10, v11
	v_lshl_add_u64 v[8:9], v[8:9], 1, s[76:77]
	v_lshl_add_u64 v[30:31], v[26:27], 0, v[146:147]
	global_store_dwordx4 v[46:47], v[42:45], off sc1
	v_cvt_pk_bf16_f32 v26, v38, v39
	v_cvt_pk_bf16_f32 v27, v40, v41
	v_cvt_pk_bf16_f32 v28, v34, v35
	v_cvt_pk_bf16_f32 v29, v36, v37
	global_store_dwordx4 v[30:31], v[12:15], off offset:256 sc1
	v_cvt_pk_bf16_f32 v10, v16, v17
	v_cvt_pk_bf16_f32 v11, v18, v19
	v_lshl_add_u64 v[12:13], v[8:9], 0, v[146:147]
	v_cvt_pk_bf16_f32 v8, v20, v21
	v_cvt_pk_bf16_f32 v9, v22, v23
	v_cvt_pk_bf16_f32 v4, v4, v5
	v_cvt_pk_bf16_f32 v5, v6, v7
	v_cvt_pk_bf16_f32 v6, v0, v1
	v_cvt_pk_bf16_f32 v7, v2, v3
	global_store_dwordx4 v[30:31], v[26:29], off sc1
	global_store_dwordx4 v[12:13], v[8:11], off sc1
	global_store_dwordx4 v[12:13], v[4:7], off offset:256 sc1
	s_and_b64 vcc, exec, s[4:5]
	s_mov_b64 s[4:5], -1
	s_cbranch_vccnz .LBB0_909
